# all GEMM K-loops: priority raised before the opening barrier, redundant lgkmcnt(0) and no-op priority flips removed from the MFMA blocks, closing barrier signalled before lowering priority; on top of
# speedup vs baseline: 1.1230x; 1.1230x over previous
.LBB0_133:
	ds_read_b128 v[150:153], v156
	ds_read_b128 v[160:163], v156 offset:1024
	ds_read_b128 v[164:167], v156 offset:2048
	ds_read_b128 v[168:171], v156 offset:3072
	ds_read_b128 v[176:179], v157
	ds_read_b128 v[180:183], v157 offset:1024
	ds_read_b128 v[184:187], v157 offset:2048
	ds_read_b128 v[188:191], v157 offset:3072
	s_add_u32 s20, s4, 0xfff00080
	s_addc_u32 s21, s5, -1
	s_cmp_eq_u32 s47, 60
	s_cselect_b32 s23, s13, s21
	s_cselect_b32 s22, s43, s20
	s_cselect_b32 s21, s11, s46
	s_cselect_b32 s20, s44, s45
	v_lshl_add_u64 v[172:173], s[4:5], 0, v[142:143]
	s_add_i32 m0, s19, 0xc000
	ds_read_b128 v[192:195], v158
	ds_read_b128 v[196:199], v158 offset:1024
	ds_read_b128 v[200:203], v158 offset:2048
	ds_read_b128 v[204:207], v158 offset:3072
	ds_read_b128 v[208:211], v158 offset:4096
	ds_read_b128 v[212:215], v158 offset:5120
	ds_read_b128 v[216:219], v158 offset:6144
	ds_read_b128 v[220:223], v158 offset:7168
	global_load_lds_dwordx4 v[172:173], off
	v_lshl_add_u64 v[172:173], s[4:5], 0, v[144:145]
	s_add_i32 m0, s19, 0xe000
	s_nop 0
	global_load_lds_dwordx4 v[172:173], off
	s_waitcnt vmcnt(8)
	s_waitcnt lgkmcnt(0)
	s_setprio 1
	s_barrier
	v_mfma_f32_16x16x32_bf16 v[126:129], v[150:153], v[192:195], v[126:129]
	v_mfma_f32_16x16x32_bf16 v[122:125], v[164:167], v[192:195], v[122:125]
	v_mfma_f32_16x16x32_bf16 v[118:121], v[150:153], v[200:203], v[118:121]
	v_mfma_f32_16x16x32_bf16 v[110:113], v[164:167], v[200:203], v[110:113]
	v_mfma_f32_16x16x32_bf16 v[102:105], v[150:153], v[208:211], v[102:105]
	v_mfma_f32_16x16x32_bf16 v[94:97], v[164:167], v[208:211], v[94:97]
	v_mfma_f32_16x16x32_bf16 v[86:89], v[150:153], v[216:219], v[86:89]
	v_mfma_f32_16x16x32_bf16 v[78:81], v[164:167], v[216:219], v[78:81]
	v_mfma_f32_16x16x32_bf16 v[126:129], v[160:163], v[196:199], v[126:129]
	v_mfma_f32_16x16x32_bf16 v[122:125], v[168:171], v[196:199], v[122:125]
	v_mfma_f32_16x16x32_bf16 v[118:121], v[160:163], v[204:207], v[118:121]
	v_mfma_f32_16x16x32_bf16 v[110:113], v[168:171], v[204:207], v[110:113]
	v_mfma_f32_16x16x32_bf16 v[102:105], v[160:163], v[212:215], v[102:105]
	v_mfma_f32_16x16x32_bf16 v[94:97], v[168:171], v[212:215], v[94:97]
	v_mfma_f32_16x16x32_bf16 v[86:89], v[160:163], v[220:223], v[86:89]
	v_mfma_f32_16x16x32_bf16 v[78:81], v[168:171], v[220:223], v[78:81]
	v_mfma_f32_16x16x32_bf16 v[114:117], v[176:179], v[192:195], v[114:117]
	v_mfma_f32_16x16x32_bf16 v[106:109], v[184:187], v[192:195], v[106:109]
	v_mfma_f32_16x16x32_bf16 v[98:101], v[176:179], v[200:203], v[98:101]
	v_mfma_f32_16x16x32_bf16 v[90:93], v[184:187], v[200:203], v[90:93]
	v_mfma_f32_16x16x32_bf16 v[82:85], v[176:179], v[208:211], v[82:85]
	v_mfma_f32_16x16x32_bf16 v[74:77], v[184:187], v[208:211], v[74:77]
	v_mfma_f32_16x16x32_bf16 v[70:73], v[176:179], v[216:219], v[70:73]
	v_mfma_f32_16x16x32_bf16 v[66:69], v[184:187], v[216:219], v[66:69]
	v_mfma_f32_16x16x32_bf16 v[114:117], v[180:183], v[196:199], v[114:117]
	v_mfma_f32_16x16x32_bf16 v[106:109], v[188:191], v[196:199], v[106:109]
	v_mfma_f32_16x16x32_bf16 v[98:101], v[180:183], v[204:207], v[98:101]
	v_mfma_f32_16x16x32_bf16 v[90:93], v[188:191], v[204:207], v[90:93]
	v_mfma_f32_16x16x32_bf16 v[82:85], v[180:183], v[212:215], v[82:85]
	v_mfma_f32_16x16x32_bf16 v[74:77], v[188:191], v[212:215], v[74:77]
	v_mfma_f32_16x16x32_bf16 v[70:73], v[180:183], v[220:223], v[70:73]
	v_mfma_f32_16x16x32_bf16 v[66:69], v[188:191], v[220:223], v[66:69]
	s_barrier
	s_setprio 0
	s_add_i32 s48, s39, s29
	v_lshl_add_u64 v[172:173], s[20:21], 0, v[132:133]
	s_mov_b32 m0, s48
	ds_read_b128 v[192:195], v158 offset:16384
	ds_read_b128 v[196:199], v158 offset:17408
	ds_read_b128 v[200:203], v158 offset:18432
	ds_read_b128 v[204:207], v158 offset:19456
	ds_read_b128 v[208:211], v158 offset:20480
	ds_read_b128 v[212:215], v158 offset:21504
	ds_read_b128 v[216:219], v158 offset:22528
	ds_read_b128 v[220:223], v158 offset:23552
	global_load_lds_dwordx4 v[172:173], off
	s_add_i32 m0, s48, 0x2000
	s_add_u32 s48, s20, 0x100000
	v_lshl_add_u64 v[224:225], s[20:21], 0, v[136:137]
	s_addc_u32 s49, s21, 0
	s_add_i32 s50, s40, s29
	global_load_lds_dwordx4 v[224:225], off
	v_lshl_add_u64 v[226:227], s[48:49], 0, v[132:133]
	s_mov_b32 m0, s50
	v_lshl_add_u64 v[228:229], s[22:23], 0, v[134:135]
	global_load_lds_dwordx4 v[226:227], off
	v_lshl_add_u64 v[226:227], s[48:49], 0, v[136:137]
	s_add_i32 m0, s50, 0x2000
	s_nop 0
	global_load_lds_dwordx4 v[226:227], off
	v_lshl_add_u64 v[226:227], s[22:23], 0, v[130:131]
	s_mov_b32 m0, s19
	s_nop 0
	global_load_lds_dwordx4 v[226:227], off
	s_mov_b32 m0, s30
	s_nop 0
	global_load_lds_dwordx4 v[228:229], off
	s_waitcnt vmcnt(8)
	s_waitcnt lgkmcnt(0)
	s_setprio 1
	s_barrier
	v_mfma_f32_16x16x32_bf16 v[62:65], v[150:153], v[192:195], v[62:65]
	v_mfma_f32_16x16x32_bf16 v[58:61], v[164:167], v[192:195], v[58:61]
	v_mfma_f32_16x16x32_bf16 v[54:57], v[150:153], v[200:203], v[54:57]
	v_mfma_f32_16x16x32_bf16 v[46:49], v[164:167], v[200:203], v[46:49]
	v_mfma_f32_16x16x32_bf16 v[38:41], v[150:153], v[208:211], v[38:41]
	v_mfma_f32_16x16x32_bf16 v[30:33], v[164:167], v[208:211], v[30:33]
	v_mfma_f32_16x16x32_bf16 v[22:25], v[150:153], v[216:219], v[22:25]
	v_mfma_f32_16x16x32_bf16 v[14:17], v[164:167], v[216:219], v[14:17]
	v_mfma_f32_16x16x32_bf16 v[62:65], v[160:163], v[196:199], v[62:65]
	v_mfma_f32_16x16x32_bf16 v[58:61], v[168:171], v[196:199], v[58:61]
	v_mfma_f32_16x16x32_bf16 v[54:57], v[160:163], v[204:207], v[54:57]
	v_mfma_f32_16x16x32_bf16 v[46:49], v[168:171], v[204:207], v[46:49]
	v_mfma_f32_16x16x32_bf16 v[38:41], v[160:163], v[212:215], v[38:41]
	v_mfma_f32_16x16x32_bf16 v[30:33], v[168:171], v[212:215], v[30:33]
	v_mfma_f32_16x16x32_bf16 v[22:25], v[160:163], v[220:223], v[22:25]
	v_mfma_f32_16x16x32_bf16 v[14:17], v[168:171], v[220:223], v[14:17]
	v_mfma_f32_16x16x32_bf16 v[50:53], v[176:179], v[192:195], v[50:53]
	v_mfma_f32_16x16x32_bf16 v[42:45], v[184:187], v[192:195], v[42:45]
	v_mfma_f32_16x16x32_bf16 v[34:37], v[176:179], v[200:203], v[34:37]
	v_mfma_f32_16x16x32_bf16 v[26:29], v[184:187], v[200:203], v[26:29]
	v_mfma_f32_16x16x32_bf16 v[18:21], v[176:179], v[208:211], v[18:21]
	v_mfma_f32_16x16x32_bf16 v[10:13], v[184:187], v[208:211], v[10:13]
	v_mfma_f32_16x16x32_bf16 v[6:9], v[176:179], v[216:219], v[6:9]
	v_mfma_f32_16x16x32_bf16 v[2:5], v[184:187], v[216:219], v[2:5]
	v_mfma_f32_16x16x32_bf16 v[50:53], v[180:183], v[196:199], v[50:53]
	v_mfma_f32_16x16x32_bf16 v[42:45], v[188:191], v[196:199], v[42:45]
	v_mfma_f32_16x16x32_bf16 v[34:37], v[180:183], v[204:207], v[34:37]
	v_mfma_f32_16x16x32_bf16 v[26:29], v[188:191], v[204:207], v[26:29]
	v_mfma_f32_16x16x32_bf16 v[18:21], v[180:183], v[212:215], v[18:21]
	v_mfma_f32_16x16x32_bf16 v[10:13], v[188:191], v[212:215], v[10:13]
	v_mfma_f32_16x16x32_bf16 v[6:9], v[180:183], v[220:223], v[6:9]
	v_mfma_f32_16x16x32_bf16 v[2:5], v[188:191], v[220:223], v[2:5]
	s_barrier
	s_setprio 0
	s_add_i32 s48, 0, 0x18000
	v_add_u32_e32 v159, s48, v154
	s_add_i32 s49, 0, 0x1c000
	ds_read_b128 v[150:153], v159
	ds_read_b128 v[160:163], v159 offset:1024
	ds_read_b128 v[164:167], v159 offset:2048
	ds_read_b128 v[168:171], v159 offset:3072
	v_add_u32_e32 v159, s49, v154
	ds_read_b128 v[176:179], v159
	ds_read_b128 v[180:183], v159 offset:1024
	ds_read_b128 v[184:187], v159 offset:2048
	ds_read_b128 v[188:191], v159 offset:3072
	s_add_u32 s22, s22, 0x100000
	s_addc_u32 s23, s23, 0
	s_mov_b32 m0, s31
	v_lshl_add_u64 v[230:231], s[22:23], 0, v[130:131]
	ds_read_b128 v[192:195], v158 offset:32768
	ds_read_b128 v[196:199], v158 offset:33792
	ds_read_b128 v[200:203], v158 offset:34816
	ds_read_b128 v[204:207], v158 offset:35840
	ds_read_b128 v[208:211], v158 offset:36864
	ds_read_b128 v[212:215], v158 offset:37888
	ds_read_b128 v[216:219], v158 offset:38912
	ds_read_b128 v[220:223], v158 offset:39936
	global_load_lds_dwordx4 v[230:231], off
	v_lshl_add_u64 v[230:231], s[22:23], 0, v[134:135]
	s_mov_b32 m0, s33
	s_nop 0
	global_load_lds_dwordx4 v[230:231], off
	s_waitcnt vmcnt(8)
	s_waitcnt lgkmcnt(0)
	s_setprio 1
	s_barrier
	v_mfma_f32_16x16x32_bf16 v[126:129], v[150:153], v[192:195], v[126:129]
	v_mfma_f32_16x16x32_bf16 v[122:125], v[164:167], v[192:195], v[122:125]
	v_mfma_f32_16x16x32_bf16 v[118:121], v[150:153], v[200:203], v[118:121]
	v_mfma_f32_16x16x32_bf16 v[110:113], v[164:167], v[200:203], v[110:113]
	v_mfma_f32_16x16x32_bf16 v[102:105], v[150:153], v[208:211], v[102:105]
	v_mfma_f32_16x16x32_bf16 v[94:97], v[164:167], v[208:211], v[94:97]
	v_mfma_f32_16x16x32_bf16 v[86:89], v[150:153], v[216:219], v[86:89]
	v_mfma_f32_16x16x32_bf16 v[78:81], v[164:167], v[216:219], v[78:81]
	v_mfma_f32_16x16x32_bf16 v[126:129], v[160:163], v[196:199], v[126:129]
	v_mfma_f32_16x16x32_bf16 v[122:125], v[168:171], v[196:199], v[122:125]
	v_mfma_f32_16x16x32_bf16 v[118:121], v[160:163], v[204:207], v[118:121]
	v_mfma_f32_16x16x32_bf16 v[110:113], v[168:171], v[204:207], v[110:113]
	v_mfma_f32_16x16x32_bf16 v[102:105], v[160:163], v[212:215], v[102:105]
	v_mfma_f32_16x16x32_bf16 v[94:97], v[168:171], v[212:215], v[94:97]
	v_mfma_f32_16x16x32_bf16 v[86:89], v[160:163], v[220:223], v[86:89]
	v_mfma_f32_16x16x32_bf16 v[78:81], v[168:171], v[220:223], v[78:81]
	v_mfma_f32_16x16x32_bf16 v[114:117], v[176:179], v[192:195], v[114:117]
	v_mfma_f32_16x16x32_bf16 v[106:109], v[184:187], v[192:195], v[106:109]
	v_mfma_f32_16x16x32_bf16 v[98:101], v[176:179], v[200:203], v[98:101]
	v_mfma_f32_16x16x32_bf16 v[90:93], v[184:187], v[200:203], v[90:93]
	v_mfma_f32_16x16x32_bf16 v[82:85], v[176:179], v[208:211], v[82:85]
	v_mfma_f32_16x16x32_bf16 v[74:77], v[184:187], v[208:211], v[74:77]
	v_mfma_f32_16x16x32_bf16 v[70:73], v[176:179], v[216:219], v[70:73]
	v_mfma_f32_16x16x32_bf16 v[66:69], v[184:187], v[216:219], v[66:69]
	v_mfma_f32_16x16x32_bf16 v[114:117], v[180:183], v[196:199], v[114:117]
	v_mfma_f32_16x16x32_bf16 v[106:109], v[188:191], v[196:199], v[106:109]
	v_mfma_f32_16x16x32_bf16 v[98:101], v[180:183], v[204:207], v[98:101]
	v_mfma_f32_16x16x32_bf16 v[90:93], v[188:191], v[204:207], v[90:93]
	v_mfma_f32_16x16x32_bf16 v[82:85], v[180:183], v[212:215], v[82:85]
	v_mfma_f32_16x16x32_bf16 v[74:77], v[188:191], v[212:215], v[74:77]
	v_mfma_f32_16x16x32_bf16 v[70:73], v[180:183], v[220:223], v[70:73]
	v_mfma_f32_16x16x32_bf16 v[66:69], v[188:191], v[220:223], v[66:69]
	s_barrier
	s_setprio 0
	s_add_i32 s22, s48, s29
	v_lshl_add_u64 v[172:173], v[172:173], 0, s[2:3]
	s_mov_b32 m0, s22
	ds_read_b128 v[192:195], v158 offset:49152
	ds_read_b128 v[196:199], v158 offset:50176
	ds_read_b128 v[200:203], v158 offset:51200
	ds_read_b128 v[204:207], v158 offset:52224
	ds_read_b128 v[208:211], v158 offset:53248
	ds_read_b128 v[212:215], v158 offset:54272
	ds_read_b128 v[216:219], v158 offset:55296
	ds_read_b128 v[220:223], v158 offset:56320
	global_load_lds_dwordx4 v[172:173], off
	s_add_i32 m0, s22, 0x2000
	s_add_u32 s20, s20, 0x100080
	v_lshl_add_u64 v[172:173], v[224:225], 0, s[2:3]
	s_addc_u32 s21, s21, 0
	s_add_i32 s22, s49, s29
	global_load_lds_dwordx4 v[172:173], off
	v_lshl_add_u64 v[172:173], s[20:21], 0, v[132:133]
	s_mov_b32 m0, s22
	s_nop 0
	global_load_lds_dwordx4 v[172:173], off
	v_lshl_add_u64 v[172:173], s[20:21], 0, v[136:137]
	s_add_i32 m0, s22, 0x2000
	s_nop 0
	global_load_lds_dwordx4 v[172:173], off
	v_lshl_add_u64 v[172:173], v[226:227], 0, s[2:3]
	s_mov_b32 m0, s35
	s_nop 0
	global_load_lds_dwordx4 v[172:173], off
	v_lshl_add_u64 v[172:173], v[228:229], 0, s[2:3]
	s_mov_b32 m0, s36
	s_nop 0
	global_load_lds_dwordx4 v[172:173], off
	s_waitcnt vmcnt(8)
	s_waitcnt lgkmcnt(0)
	s_setprio 1
	s_barrier
	v_mfma_f32_16x16x32_bf16 v[62:65], v[150:153], v[192:195], v[62:65]
	v_mfma_f32_16x16x32_bf16 v[58:61], v[164:167], v[192:195], v[58:61]
	v_mfma_f32_16x16x32_bf16 v[54:57], v[150:153], v[200:203], v[54:57]
	v_mfma_f32_16x16x32_bf16 v[46:49], v[164:167], v[200:203], v[46:49]
	v_mfma_f32_16x16x32_bf16 v[38:41], v[150:153], v[208:211], v[38:41]
	v_mfma_f32_16x16x32_bf16 v[30:33], v[164:167], v[208:211], v[30:33]
	v_mfma_f32_16x16x32_bf16 v[22:25], v[150:153], v[216:219], v[22:25]
	v_mfma_f32_16x16x32_bf16 v[14:17], v[164:167], v[216:219], v[14:17]
	v_mfma_f32_16x16x32_bf16 v[62:65], v[160:163], v[196:199], v[62:65]
	v_mfma_f32_16x16x32_bf16 v[58:61], v[168:171], v[196:199], v[58:61]
	v_mfma_f32_16x16x32_bf16 v[54:57], v[160:163], v[204:207], v[54:57]
	v_mfma_f32_16x16x32_bf16 v[46:49], v[168:171], v[204:207], v[46:49]
	v_mfma_f32_16x16x32_bf16 v[38:41], v[160:163], v[212:215], v[38:41]
	v_mfma_f32_16x16x32_bf16 v[30:33], v[168:171], v[212:215], v[30:33]
	v_mfma_f32_16x16x32_bf16 v[22:25], v[160:163], v[220:223], v[22:25]
	v_mfma_f32_16x16x32_bf16 v[14:17], v[168:171], v[220:223], v[14:17]
	v_mfma_f32_16x16x32_bf16 v[50:53], v[176:179], v[192:195], v[50:53]
	v_mfma_f32_16x16x32_bf16 v[42:45], v[184:187], v[192:195], v[42:45]
	v_mfma_f32_16x16x32_bf16 v[34:37], v[176:179], v[200:203], v[34:37]
	v_mfma_f32_16x16x32_bf16 v[26:29], v[184:187], v[200:203], v[26:29]
	v_mfma_f32_16x16x32_bf16 v[18:21], v[176:179], v[208:211], v[18:21]
	v_mfma_f32_16x16x32_bf16 v[10:13], v[184:187], v[208:211], v[10:13]
	v_mfma_f32_16x16x32_bf16 v[6:9], v[176:179], v[216:219], v[6:9]
	v_mfma_f32_16x16x32_bf16 v[2:5], v[184:187], v[216:219], v[2:5]
	v_mfma_f32_16x16x32_bf16 v[50:53], v[180:183], v[196:199], v[50:53]
	v_mfma_f32_16x16x32_bf16 v[42:45], v[188:191], v[196:199], v[42:45]
	v_mfma_f32_16x16x32_bf16 v[34:37], v[180:183], v[204:207], v[34:37]
	v_mfma_f32_16x16x32_bf16 v[26:29], v[188:191], v[204:207], v[26:29]
	v_mfma_f32_16x16x32_bf16 v[18:21], v[180:183], v[212:215], v[18:21]
	v_mfma_f32_16x16x32_bf16 v[10:13], v[188:191], v[212:215], v[10:13]
	v_mfma_f32_16x16x32_bf16 v[6:9], v[180:183], v[220:223], v[6:9]
	v_mfma_f32_16x16x32_bf16 v[2:5], v[188:191], v[220:223], v[2:5]
	s_barrier
	s_setprio 0
	s_add_i32 s47, s47, 2
	s_add_u32 s4, s4, 0x100
	s_addc_u32 s5, s5, 0
	s_add_u32 s45, s45, 0x100
	s_addc_u32 s46, s46, 0
	s_cmp_gt_u32 s47, 61
	s_cbranch_scc0 .LBB0_133
	v_lshl_add_u32 v150, s18, 8, v1
	s_cmp_gt_i32 s42, 7
	s_mov_b64 s[4:5], -1
	s_cbranch_scc0 .LBB0_142
	s_cmp_gt_u32 s42, 31
	s_cbranch_scc0 .LBB0_139
	s_andn2_b64 vcc, exec, s[8:9]
	s_cbranch_vccnz .LBB0_138
	v_or_b32_e32 v160, 16, v150
	v_ashrrev_i32_e32 v151, 31, v150
	v_ashrrev_i32_e32 v161, 31, v160
	v_lshlrev_b64 v[152:153], 7, v[150:151]
	v_lshlrev_b64 v[160:161], 7, v[160:161]
	v_lshl_add_u64 v[152:153], v[138:139], 0, v[152:153]
	v_lshl_add_u64 v[160:161], v[138:139], 0, v[160:161]
	global_store_dwordx4 v[152:153], v[126:129], off
	global_store_dwordx4 v[152:153], v[122:125], off offset:16
	global_store_dwordx4 v[160:161], v[118:121], off
	global_store_dwordx4 v[160:161], v[110:113], off offset:16
	v_or_b32_e32 v160, 32, v150
	v_ashrrev_i32_e32 v161, 31, v160
	v_lshlrev_b64 v[160:161], 7, v[160:161]
	v_lshl_add_u64 v[160:161], v[138:139], 0, v[160:161]
	global_store_dwordx4 v[160:161], v[102:105], off
	global_store_dwordx4 v[160:161], v[94:97], off offset:16
	v_or_b32_e32 v160, 48, v150
	v_ashrrev_i32_e32 v161, 31, v160
	v_lshlrev_b64 v[160:161], 7, v[160:161]
	v_lshl_add_u64 v[160:161], v[138:139], 0, v[160:161]
	s_mov_b64 s[4:5], 0x4000
	global_store_dwordx4 v[160:161], v[86:89], off
	global_store_dwordx4 v[160:161], v[78:81], off offset:16
	v_lshl_add_u64 v[160:161], v[152:153], 0, s[4:5]
	s_movk_i32 s4, 0x4000
	v_add_co_u32_e32 v162, vcc, s4, v152
	s_mov_b64 s[4:5], 0x4800
	s_nop 0
	v_addc_co_u32_e32 v163, vcc, 0, v153, vcc
	global_store_dwordx4 v[162:163], v[62:65], off
	global_store_dwordx4 v[160:161], v[58:61], off offset:16
	v_lshl_add_u64 v[160:161], v[152:153], 0, s[4:5]
	global_store_dwordx4 v[162:163], v[54:57], off offset:2048
	global_store_dwordx4 v[160:161], v[46:49], off offset:16
	s_mov_b64 s[4:5], 0x5000
	v_add_co_u32_e32 v162, vcc, 0x5000, v152
	v_lshl_add_u64 v[160:161], v[152:153], 0, s[4:5]
	s_nop 0
	v_addc_co_u32_e32 v163, vcc, 0, v153, vcc
	s_mov_b64 s[4:5], 0x5800
	global_store_dwordx4 v[162:163], v[38:41], off
	global_store_dwordx4 v[160:161], v[30:33], off offset:16
	v_lshl_add_u64 v[152:153], v[152:153], 0, s[4:5]
	global_store_dwordx4 v[162:163], v[22:25], off offset:2048
	global_store_dwordx4 v[152:153], v[14:17], off offset:16

.LBB0_508:
	ds_read_b128 v[58:61], v168
	ds_read_b128 v[62:65], v168 offset:1024
	ds_read_b128 v[74:77], v168 offset:2048
	ds_read_b128 v[78:81], v168 offset:3072
	ds_read_b128 v[162:165], v169
	ds_read_b128 v[176:179], v169 offset:1024
	ds_read_b128 v[180:183], v169 offset:2048
	ds_read_b128 v[184:187], v169 offset:3072
	s_add_u32 s20, s0, 0xfff80080
	s_addc_u32 s21, s1, -1
	s_cmp_eq_u32 s44, 28
	s_cselect_b32 s23, s17, s21
	s_cselect_b32 s22, s40, s20
	s_cselect_b32 s21, s3, s43
	s_cselect_b32 s20, s41, s42
	v_lshl_add_u64 v[172:173], s[0:1], 0, v[154:155]
	s_add_i32 m0, s19, 0xc000
	ds_read_b128 v[188:191], v170
	ds_read_b128 v[192:195], v170 offset:1024
	ds_read_b128 v[196:199], v170 offset:2048
	ds_read_b128 v[200:203], v170 offset:3072
	ds_read_b128 v[204:207], v170 offset:4096
	ds_read_b128 v[208:211], v170 offset:5120
	ds_read_b128 v[212:215], v170 offset:6144
	ds_read_b128 v[216:219], v170 offset:7168
	global_load_lds_dwordx4 v[172:173], off
	v_lshl_add_u64 v[172:173], s[0:1], 0, v[156:157]
	s_add_i32 m0, s19, 0xe000
	s_nop 0
	global_load_lds_dwordx4 v[172:173], off
	s_waitcnt vmcnt(8)
	s_waitcnt lgkmcnt(0)
	s_setprio 1
	s_barrier
	v_mfma_f32_16x16x32_bf16 v[142:145], v[58:61], v[188:191], v[142:145]
	v_mfma_f32_16x16x32_bf16 v[138:141], v[74:77], v[188:191], v[138:141]
	v_mfma_f32_16x16x32_bf16 v[126:129], v[58:61], v[196:199], v[126:129]
	v_mfma_f32_16x16x32_bf16 v[122:125], v[74:77], v[196:199], v[122:125]
	v_mfma_f32_16x16x32_bf16 v[110:113], v[58:61], v[204:207], v[110:113]
	v_mfma_f32_16x16x32_bf16 v[106:109], v[74:77], v[204:207], v[106:109]
	v_mfma_f32_16x16x32_bf16 v[94:97], v[58:61], v[212:215], v[94:97]
	v_mfma_f32_16x16x32_bf16 v[90:93], v[74:77], v[212:215], v[90:93]
	v_mfma_f32_16x16x32_bf16 v[142:145], v[62:65], v[192:195], v[142:145]
	v_mfma_f32_16x16x32_bf16 v[138:141], v[78:81], v[192:195], v[138:141]
	v_mfma_f32_16x16x32_bf16 v[126:129], v[62:65], v[200:203], v[126:129]
	v_mfma_f32_16x16x32_bf16 v[122:125], v[78:81], v[200:203], v[122:125]
	v_mfma_f32_16x16x32_bf16 v[110:113], v[62:65], v[208:211], v[110:113]
	v_mfma_f32_16x16x32_bf16 v[106:109], v[78:81], v[208:211], v[106:109]
	v_mfma_f32_16x16x32_bf16 v[94:97], v[62:65], v[216:219], v[94:97]
	v_mfma_f32_16x16x32_bf16 v[90:93], v[78:81], v[216:219], v[90:93]
	v_mfma_f32_16x16x32_bf16 v[134:137], v[162:165], v[188:191], v[134:137]
	v_mfma_f32_16x16x32_bf16 v[130:133], v[180:183], v[188:191], v[130:133]
	v_mfma_f32_16x16x32_bf16 v[118:121], v[162:165], v[196:199], v[118:121]
	v_mfma_f32_16x16x32_bf16 v[114:117], v[180:183], v[196:199], v[114:117]
	v_mfma_f32_16x16x32_bf16 v[102:105], v[162:165], v[204:207], v[102:105]
	v_mfma_f32_16x16x32_bf16 v[98:101], v[180:183], v[204:207], v[98:101]
	v_mfma_f32_16x16x32_bf16 v[86:89], v[162:165], v[212:215], v[86:89]
	v_mfma_f32_16x16x32_bf16 v[82:85], v[180:183], v[212:215], v[82:85]
	v_mfma_f32_16x16x32_bf16 v[134:137], v[176:179], v[192:195], v[134:137]
	v_mfma_f32_16x16x32_bf16 v[130:133], v[184:187], v[192:195], v[130:133]
	v_mfma_f32_16x16x32_bf16 v[118:121], v[176:179], v[200:203], v[118:121]
	v_mfma_f32_16x16x32_bf16 v[114:117], v[184:187], v[200:203], v[114:117]
	v_mfma_f32_16x16x32_bf16 v[102:105], v[176:179], v[208:211], v[102:105]
	v_mfma_f32_16x16x32_bf16 v[98:101], v[184:187], v[208:211], v[98:101]
	v_mfma_f32_16x16x32_bf16 v[86:89], v[176:179], v[216:219], v[86:89]
	v_mfma_f32_16x16x32_bf16 v[82:85], v[184:187], v[216:219], v[82:85]
	s_barrier
	s_setprio 0
	s_add_i32 s45, s37, s27
	v_lshl_add_u64 v[172:173], s[20:21], 0, v[150:151]
	s_mov_b32 m0, s45
	ds_read_b128 v[188:191], v170 offset:16384
	ds_read_b128 v[192:195], v170 offset:17408
	ds_read_b128 v[196:199], v170 offset:18432
	ds_read_b128 v[200:203], v170 offset:19456
	ds_read_b128 v[204:207], v170 offset:20480
	ds_read_b128 v[208:211], v170 offset:21504
	ds_read_b128 v[212:215], v170 offset:22528
	ds_read_b128 v[216:219], v170 offset:23552
	global_load_lds_dwordx4 v[172:173], off
	s_add_i32 m0, s45, 0x2000
	s_add_u32 s46, s20, 0x80000
	v_lshl_add_u64 v[220:221], s[20:21], 0, v[146:147]
	s_addc_u32 s47, s21, 0
	s_add_i32 s45, s38, s27
	global_load_lds_dwordx4 v[220:221], off
	v_lshl_add_u64 v[222:223], s[46:47], 0, v[150:151]
	s_mov_b32 m0, s45
	v_lshl_add_u64 v[224:225], s[22:23], 0, v[148:149]
	global_load_lds_dwordx4 v[222:223], off
	v_lshl_add_u64 v[222:223], s[46:47], 0, v[146:147]
	s_add_i32 m0, s45, 0x2000
	s_nop 0
	global_load_lds_dwordx4 v[222:223], off
	v_lshl_add_u64 v[222:223], s[22:23], 0, v[152:153]
	s_mov_b32 m0, s19
	s_nop 0
	global_load_lds_dwordx4 v[222:223], off
	s_mov_b32 m0, s28
	s_nop 0
	global_load_lds_dwordx4 v[224:225], off
	s_waitcnt vmcnt(8)
	s_waitcnt lgkmcnt(0)
	s_setprio 1
	s_barrier
	v_mfma_f32_16x16x32_bf16 v[70:73], v[58:61], v[188:191], v[70:73]
	v_mfma_f32_16x16x32_bf16 v[66:69], v[74:77], v[188:191], v[66:69]
	v_mfma_f32_16x16x32_bf16 v[46:49], v[58:61], v[196:199], v[46:49]
	v_mfma_f32_16x16x32_bf16 v[42:45], v[74:77], v[196:199], v[42:45]
	v_mfma_f32_16x16x32_bf16 v[30:33], v[58:61], v[204:207], v[30:33]
	v_mfma_f32_16x16x32_bf16 v[26:29], v[74:77], v[204:207], v[26:29]
	v_mfma_f32_16x16x32_bf16 v[14:17], v[58:61], v[212:215], v[14:17]
	v_mfma_f32_16x16x32_bf16 v[10:13], v[74:77], v[212:215], v[10:13]
	v_mfma_f32_16x16x32_bf16 v[70:73], v[62:65], v[192:195], v[70:73]
	v_mfma_f32_16x16x32_bf16 v[66:69], v[78:81], v[192:195], v[66:69]
	v_mfma_f32_16x16x32_bf16 v[46:49], v[62:65], v[200:203], v[46:49]
	v_mfma_f32_16x16x32_bf16 v[42:45], v[78:81], v[200:203], v[42:45]
	v_mfma_f32_16x16x32_bf16 v[30:33], v[62:65], v[208:211], v[30:33]
	v_mfma_f32_16x16x32_bf16 v[26:29], v[78:81], v[208:211], v[26:29]
	v_mfma_f32_16x16x32_bf16 v[14:17], v[62:65], v[216:219], v[14:17]
	v_mfma_f32_16x16x32_bf16 v[10:13], v[78:81], v[216:219], v[10:13]
	v_mfma_f32_16x16x32_bf16 v[54:57], v[162:165], v[188:191], v[54:57]
	v_mfma_f32_16x16x32_bf16 v[50:53], v[180:183], v[188:191], v[50:53]
	v_mfma_f32_16x16x32_bf16 v[38:41], v[162:165], v[196:199], v[38:41]
	v_mfma_f32_16x16x32_bf16 v[34:37], v[180:183], v[196:199], v[34:37]
	v_mfma_f32_16x16x32_bf16 v[22:25], v[162:165], v[204:207], v[22:25]
	v_mfma_f32_16x16x32_bf16 v[18:21], v[180:183], v[204:207], v[18:21]
	v_mfma_f32_16x16x32_bf16 v[6:9], v[162:165], v[212:215], v[6:9]
	v_mfma_f32_16x16x32_bf16 v[2:5], v[180:183], v[212:215], v[2:5]
	v_mfma_f32_16x16x32_bf16 v[54:57], v[176:179], v[192:195], v[54:57]
	v_mfma_f32_16x16x32_bf16 v[50:53], v[184:187], v[192:195], v[50:53]
	v_mfma_f32_16x16x32_bf16 v[38:41], v[176:179], v[200:203], v[38:41]
	v_mfma_f32_16x16x32_bf16 v[34:37], v[184:187], v[200:203], v[34:37]
	v_mfma_f32_16x16x32_bf16 v[22:25], v[176:179], v[208:211], v[22:25]
	v_mfma_f32_16x16x32_bf16 v[18:21], v[184:187], v[208:211], v[18:21]
	v_mfma_f32_16x16x32_bf16 v[6:9], v[176:179], v[216:219], v[6:9]
	v_mfma_f32_16x16x32_bf16 v[2:5], v[184:187], v[216:219], v[2:5]
	s_barrier
	s_setprio 0
	s_add_i32 s45, 0, 0x18000
	s_add_i32 s46, 0, 0x1c000
	v_add_u32_e32 v78, s45, v166
	v_add_u32_e32 v171, s46, v166
	ds_read_b128 v[58:61], v78
	ds_read_b128 v[62:65], v78 offset:1024
	ds_read_b128 v[74:77], v78 offset:2048
	ds_read_b128 v[78:81], v78 offset:3072
	ds_read_b128 v[162:165], v171
	ds_read_b128 v[176:179], v171 offset:1024
	ds_read_b128 v[180:183], v171 offset:2048
	ds_read_b128 v[184:187], v171 offset:3072
	s_add_u32 s22, s22, 0x80000
	s_addc_u32 s23, s23, 0
	s_mov_b32 m0, s29
	v_lshl_add_u64 v[226:227], s[22:23], 0, v[152:153]
	ds_read_b128 v[188:191], v170 offset:32768
	ds_read_b128 v[192:195], v170 offset:33792
	ds_read_b128 v[196:199], v170 offset:34816
	ds_read_b128 v[200:203], v170 offset:35840
	ds_read_b128 v[204:207], v170 offset:36864
	ds_read_b128 v[208:211], v170 offset:37888
	ds_read_b128 v[212:215], v170 offset:38912
	ds_read_b128 v[216:219], v170 offset:39936
	global_load_lds_dwordx4 v[226:227], off
	v_lshl_add_u64 v[226:227], s[22:23], 0, v[148:149]
	s_mov_b32 m0, s30
	s_nop 0
	global_load_lds_dwordx4 v[226:227], off
	s_waitcnt vmcnt(8)
	s_waitcnt lgkmcnt(0)
	s_setprio 1
	s_barrier
	v_mfma_f32_16x16x32_bf16 v[142:145], v[58:61], v[188:191], v[142:145]
	v_mfma_f32_16x16x32_bf16 v[138:141], v[74:77], v[188:191], v[138:141]
	v_mfma_f32_16x16x32_bf16 v[126:129], v[58:61], v[196:199], v[126:129]
	v_mfma_f32_16x16x32_bf16 v[122:125], v[74:77], v[196:199], v[122:125]
	v_mfma_f32_16x16x32_bf16 v[110:113], v[58:61], v[204:207], v[110:113]
	v_mfma_f32_16x16x32_bf16 v[106:109], v[74:77], v[204:207], v[106:109]
	v_mfma_f32_16x16x32_bf16 v[94:97], v[58:61], v[212:215], v[94:97]
	v_mfma_f32_16x16x32_bf16 v[90:93], v[74:77], v[212:215], v[90:93]
	v_mfma_f32_16x16x32_bf16 v[142:145], v[62:65], v[192:195], v[142:145]
	v_mfma_f32_16x16x32_bf16 v[138:141], v[78:81], v[192:195], v[138:141]
	v_mfma_f32_16x16x32_bf16 v[126:129], v[62:65], v[200:203], v[126:129]
	v_mfma_f32_16x16x32_bf16 v[122:125], v[78:81], v[200:203], v[122:125]
	v_mfma_f32_16x16x32_bf16 v[110:113], v[62:65], v[208:211], v[110:113]
	v_mfma_f32_16x16x32_bf16 v[106:109], v[78:81], v[208:211], v[106:109]
	v_mfma_f32_16x16x32_bf16 v[94:97], v[62:65], v[216:219], v[94:97]
	v_mfma_f32_16x16x32_bf16 v[90:93], v[78:81], v[216:219], v[90:93]
	v_mfma_f32_16x16x32_bf16 v[134:137], v[162:165], v[188:191], v[134:137]
	v_mfma_f32_16x16x32_bf16 v[130:133], v[180:183], v[188:191], v[130:133]
	v_mfma_f32_16x16x32_bf16 v[118:121], v[162:165], v[196:199], v[118:121]
	v_mfma_f32_16x16x32_bf16 v[114:117], v[180:183], v[196:199], v[114:117]
	v_mfma_f32_16x16x32_bf16 v[102:105], v[162:165], v[204:207], v[102:105]
	v_mfma_f32_16x16x32_bf16 v[98:101], v[180:183], v[204:207], v[98:101]
	v_mfma_f32_16x16x32_bf16 v[86:89], v[162:165], v[212:215], v[86:89]
	v_mfma_f32_16x16x32_bf16 v[82:85], v[180:183], v[212:215], v[82:85]
	v_mfma_f32_16x16x32_bf16 v[134:137], v[176:179], v[192:195], v[134:137]
	v_mfma_f32_16x16x32_bf16 v[130:133], v[184:187], v[192:195], v[130:133]
	v_mfma_f32_16x16x32_bf16 v[118:121], v[176:179], v[200:203], v[118:121]
	v_mfma_f32_16x16x32_bf16 v[114:117], v[184:187], v[200:203], v[114:117]
	v_mfma_f32_16x16x32_bf16 v[102:105], v[176:179], v[208:211], v[102:105]
	v_mfma_f32_16x16x32_bf16 v[98:101], v[184:187], v[208:211], v[98:101]
	v_mfma_f32_16x16x32_bf16 v[86:89], v[176:179], v[216:219], v[86:89]
	v_mfma_f32_16x16x32_bf16 v[82:85], v[184:187], v[216:219], v[82:85]
	s_barrier
	s_setprio 0
	s_add_i32 s22, s45, s27
	v_lshl_add_u64 v[172:173], v[172:173], 0, s[14:15]
	s_mov_b32 m0, s22
	ds_read_b128 v[188:191], v170 offset:49152
	ds_read_b128 v[192:195], v170 offset:50176
	ds_read_b128 v[196:199], v170 offset:51200
	ds_read_b128 v[200:203], v170 offset:52224
	ds_read_b128 v[204:207], v170 offset:53248
	ds_read_b128 v[208:211], v170 offset:54272
	ds_read_b128 v[212:215], v170 offset:55296
	ds_read_b128 v[216:219], v170 offset:56320
	global_load_lds_dwordx4 v[172:173], off
	s_add_i32 m0, s22, 0x2000
	s_add_u32 s20, s20, 0x80080
	v_lshl_add_u64 v[172:173], v[220:221], 0, s[14:15]
	s_addc_u32 s21, s21, 0
	s_add_i32 s22, s46, s27
	global_load_lds_dwordx4 v[172:173], off
	v_lshl_add_u64 v[172:173], s[20:21], 0, v[150:151]
	s_mov_b32 m0, s22
	s_nop 0
	global_load_lds_dwordx4 v[172:173], off
	v_lshl_add_u64 v[172:173], s[20:21], 0, v[146:147]
	s_add_i32 m0, s22, 0x2000
	s_nop 0
	global_load_lds_dwordx4 v[172:173], off
	v_lshl_add_u64 v[172:173], v[222:223], 0, s[14:15]
	s_mov_b32 m0, s33
	s_nop 0
	global_load_lds_dwordx4 v[172:173], off
	v_lshl_add_u64 v[172:173], v[224:225], 0, s[14:15]
	s_mov_b32 m0, s34
	s_nop 0
	global_load_lds_dwordx4 v[172:173], off
	s_waitcnt vmcnt(8)
	s_waitcnt lgkmcnt(0)
	s_setprio 1
	s_barrier
	v_mfma_f32_16x16x32_bf16 v[70:73], v[58:61], v[188:191], v[70:73]
	v_mfma_f32_16x16x32_bf16 v[66:69], v[74:77], v[188:191], v[66:69]
	v_mfma_f32_16x16x32_bf16 v[46:49], v[58:61], v[196:199], v[46:49]
	v_mfma_f32_16x16x32_bf16 v[42:45], v[74:77], v[196:199], v[42:45]
	v_mfma_f32_16x16x32_bf16 v[30:33], v[58:61], v[204:207], v[30:33]
	v_mfma_f32_16x16x32_bf16 v[26:29], v[74:77], v[204:207], v[26:29]
	v_mfma_f32_16x16x32_bf16 v[14:17], v[58:61], v[212:215], v[14:17]
	v_mfma_f32_16x16x32_bf16 v[10:13], v[74:77], v[212:215], v[10:13]
	v_mfma_f32_16x16x32_bf16 v[70:73], v[62:65], v[192:195], v[70:73]
	v_mfma_f32_16x16x32_bf16 v[66:69], v[78:81], v[192:195], v[66:69]
	v_mfma_f32_16x16x32_bf16 v[46:49], v[62:65], v[200:203], v[46:49]
	v_mfma_f32_16x16x32_bf16 v[42:45], v[78:81], v[200:203], v[42:45]
	v_mfma_f32_16x16x32_bf16 v[30:33], v[62:65], v[208:211], v[30:33]
	v_mfma_f32_16x16x32_bf16 v[26:29], v[78:81], v[208:211], v[26:29]
	v_mfma_f32_16x16x32_bf16 v[14:17], v[62:65], v[216:219], v[14:17]
	v_mfma_f32_16x16x32_bf16 v[10:13], v[78:81], v[216:219], v[10:13]
	v_mfma_f32_16x16x32_bf16 v[54:57], v[162:165], v[188:191], v[54:57]
	v_mfma_f32_16x16x32_bf16 v[50:53], v[180:183], v[188:191], v[50:53]
	v_mfma_f32_16x16x32_bf16 v[38:41], v[162:165], v[196:199], v[38:41]
	v_mfma_f32_16x16x32_bf16 v[34:37], v[180:183], v[196:199], v[34:37]
	v_mfma_f32_16x16x32_bf16 v[22:25], v[162:165], v[204:207], v[22:25]
	v_mfma_f32_16x16x32_bf16 v[18:21], v[180:183], v[204:207], v[18:21]
	v_mfma_f32_16x16x32_bf16 v[6:9], v[162:165], v[212:215], v[6:9]
	v_mfma_f32_16x16x32_bf16 v[2:5], v[180:183], v[212:215], v[2:5]
	v_mfma_f32_16x16x32_bf16 v[54:57], v[176:179], v[192:195], v[54:57]
	v_mfma_f32_16x16x32_bf16 v[50:53], v[184:187], v[192:195], v[50:53]
	v_mfma_f32_16x16x32_bf16 v[38:41], v[176:179], v[200:203], v[38:41]
	v_mfma_f32_16x16x32_bf16 v[34:37], v[184:187], v[200:203], v[34:37]
	v_mfma_f32_16x16x32_bf16 v[22:25], v[176:179], v[208:211], v[22:25]
	v_mfma_f32_16x16x32_bf16 v[18:21], v[184:187], v[208:211], v[18:21]
	v_mfma_f32_16x16x32_bf16 v[6:9], v[176:179], v[216:219], v[6:9]
	v_mfma_f32_16x16x32_bf16 v[2:5], v[184:187], v[216:219], v[2:5]
	s_barrier
	s_setprio 0
	s_add_i32 s44, s44, 2
	s_add_u32 s0, s0, 0x100
	s_addc_u32 s1, s1, 0
	s_add_u32 s42, s42, 0x100
	s_addc_u32 s43, s43, 0
	s_cmp_gt_u32 s44, 29
	s_cbranch_scc0 .LBB0_508
	v_lshl_or_b32 v58, s39, 8, v167
	v_readlane_b32 s60, v243, 17
	v_ashrrev_i32_e32 v59, 31, v58
	v_readlane_b32 s70, v243, 27
	v_readlane_b32 s71, v243, 28
	v_lshl_add_u32 v164, s18, 8, v1
	v_ashrrev_i32_e32 v165, 31, v164
	v_lshl_add_u64 v[62:63], v[58:59], 2, s[70:71]
	global_load_dwordx4 v[78:81], v[62:63], off
	global_load_dwordx4 v[74:77], v[62:63], off offset:16
	v_lshlrev_b64 v[60:61], 12, v[164:165]
	v_lshlrev_b64 v[162:163], 1, v[58:59]
	v_lshl_add_u64 v[58:59], s[6:7], 0, v[60:61]
	v_lshl_add_u64 v[172:173], v[58:59], 0, v[162:163]
	global_load_dwordx4 v[176:179], v[172:173], off
	global_load_dwordx4 v[58:61], v[62:63], off offset:528
	s_nop 0
	global_load_dwordx4 v[62:65], v[62:63], off offset:512
	s_and_b64 vcc, exec, vcc
	s_mov_b32 s18, s16
	s_mov_b32 s39, s2
	v_readlane_b32 s61, v243, 18
	v_readlane_b32 s62, v243, 19
	v_readlane_b32 s63, v243, 20
	v_readlane_b32 s64, v243, 21
	v_readlane_b32 s65, v243, 22
	v_readlane_b32 s66, v243, 23
	v_readlane_b32 s67, v243, 24
	v_readlane_b32 s68, v243, 25
	v_readlane_b32 s69, v243, 26
	v_readlane_b32 s72, v243, 29
	v_readlane_b32 s73, v243, 30
	v_readlane_b32 s74, v243, 31
	v_readlane_b32 s75, v243, 32
	s_waitcnt vmcnt(0)
	v_pk_add_f32 v[144:145], v[144:145], v[80:81]
	v_pk_add_f32 v[142:143], v[142:143], v[78:79]
	v_pk_add_f32 v[140:141], v[140:141], v[76:77]
	v_pk_add_f32 v[138:139], v[138:139], v[74:75]
	v_mul_f32_e32 v142, 0xbfb8aa3b, v142
	v_mul_f32_e32 v138, 0xbfb8aa3b, v138
	v_mul_f32_e32 v143, 0xbfb8aa3b, v143
	v_mul_f32_e32 v139, 0xbfb8aa3b, v139
	v_mul_f32_e32 v144, 0xbfb8aa3b, v144
	v_mul_f32_e32 v140, 0xbfb8aa3b, v140
	v_mul_f32_e32 v145, 0xbfb8aa3b, v145
	v_mul_f32_e32 v141, 0xbfb8aa3b, v141
	v_exp_f32_e32 v142, v142
	v_exp_f32_e32 v138, v138
	v_exp_f32_e32 v143, v143
	v_exp_f32_e32 v139, v139
	v_exp_f32_e32 v144, v144
	v_exp_f32_e32 v140, v140
	v_exp_f32_e32 v145, v145
	v_exp_f32_e32 v141, v141
	v_add_f32_e32 v142, 1.0, v142
	v_add_f32_e32 v138, 1.0, v138
	v_add_f32_e32 v143, 1.0, v143
	v_add_f32_e32 v139, 1.0, v139
	v_add_f32_e32 v144, 1.0, v144
	v_add_f32_e32 v140, 1.0, v140
	v_add_f32_e32 v145, 1.0, v145
	v_add_f32_e32 v141, 1.0, v141
	v_rcp_f32_e32 v142, v142
	v_rcp_f32_e32 v138, v138
	v_rcp_f32_e32 v143, v143
	v_rcp_f32_e32 v139, v139
	v_rcp_f32_e32 v144, v144
	v_rcp_f32_e32 v140, v140
	v_rcp_f32_e32 v145, v145
	v_rcp_f32_e32 v141, v141
	v_lshlrev_b32_e32 v171, 16, v176
	v_and_b32_e32 v175, 0xffff0000, v176
	v_lshlrev_b32_e32 v176, 16, v177
	v_and_b32_e32 v177, 0xffff0000, v177
	v_lshlrev_b32_e32 v180, 16, v178
	v_and_b32_e32 v178, 0xffff0000, v178
	v_lshlrev_b32_e32 v181, 16, v179
	v_and_b32_e32 v179, 0xffff0000, v179
	v_mul_f32_e32 v142, v142, v171
	v_mul_f32_e32 v171, v138, v180
	v_mul_f32_e32 v138, v143, v175
	v_mul_f32_e32 v143, v139, v178
	v_mul_f32_e32 v139, v144, v176
	v_mul_f32_e32 v144, v140, v181
	v_mul_f32_e32 v140, v145, v177
	v_mul_f32_e32 v141, v141, v179
	v_cvt_pk_bf16_f32 v138, v142, v138
	v_cvt_pk_bf16_f32 v139, v139, v140
	v_cvt_pk_bf16_f32 v140, v171, v143
	v_cvt_pk_bf16_f32 v141, v144, v141
	global_load_dwordx4 v[142:145], v[172:173], off offset:256
	v_pk_add_f32 v[136:137], v[136:137], v[64:65]
	v_pk_add_f32 v[134:135], v[134:135], v[62:63]
	v_pk_add_f32 v[132:133], v[132:133], v[60:61]
	v_pk_add_f32 v[130:131], v[130:131], v[58:59]
	v_mul_f32_e32 v134, 0xbfb8aa3b, v134
	v_mul_f32_e32 v130, 0xbfb8aa3b, v130
	v_mul_f32_e32 v135, 0xbfb8aa3b, v135
	v_mul_f32_e32 v131, 0xbfb8aa3b, v131
	v_mul_f32_e32 v136, 0xbfb8aa3b, v136
	v_mul_f32_e32 v132, 0xbfb8aa3b, v132
	v_mul_f32_e32 v137, 0xbfb8aa3b, v137
	v_mul_f32_e32 v133, 0xbfb8aa3b, v133
	v_exp_f32_e32 v134, v134
	v_exp_f32_e32 v130, v130
	v_exp_f32_e32 v135, v135
	v_exp_f32_e32 v131, v131
	v_exp_f32_e32 v136, v136
	v_exp_f32_e32 v132, v132
	v_exp_f32_e32 v137, v137
	v_exp_f32_e32 v133, v133
	v_add_f32_e32 v134, 1.0, v134
	v_add_f32_e32 v130, 1.0, v130
	v_add_f32_e32 v135, 1.0, v135
	v_add_f32_e32 v131, 1.0, v131
	v_add_f32_e32 v136, 1.0, v136
	v_add_f32_e32 v132, 1.0, v132
	v_add_f32_e32 v137, 1.0, v137
	v_add_f32_e32 v133, 1.0, v133
	v_or_b32_e32 v172, 16, v164
	v_lshlrev_b64 v[176:177], 13, v[164:165]
	v_rcp_f32_e32 v134, v134
	v_rcp_f32_e32 v130, v130
	v_rcp_f32_e32 v135, v135
	v_rcp_f32_e32 v131, v131
	v_rcp_f32_e32 v136, v136
	v_rcp_f32_e32 v132, v132
	v_rcp_f32_e32 v137, v137
	v_rcp_f32_e32 v133, v133
	v_ashrrev_i32_e32 v173, 31, v172
	v_lshl_add_u64 v[176:177], s[12:13], 0, v[176:177]
	v_lshlrev_b64 v[178:179], 12, v[172:173]
	v_lshl_add_u64 v[176:177], v[176:177], 0, v[162:163]
	v_lshl_add_u64 v[178:179], s[6:7], 0, v[178:179]
	global_store_dwordx4 v[176:177], v[138:141], off
	v_lshl_add_u64 v[178:179], v[178:179], 0, v[162:163]
	v_pk_add_f32 v[128:129], v[128:129], v[80:81]
	v_pk_add_f32 v[126:127], v[126:127], v[78:79]
	v_pk_add_f32 v[124:125], v[124:125], v[76:77]
	v_pk_add_f32 v[122:123], v[122:123], v[74:75]
	v_mul_f32_e32 v126, 0xbfb8aa3b, v126
	v_mul_f32_e32 v122, 0xbfb8aa3b, v122
	v_mul_f32_e32 v127, 0xbfb8aa3b, v127
	v_mul_f32_e32 v123, 0xbfb8aa3b, v123
	v_mul_f32_e32 v128, 0xbfb8aa3b, v128
	v_mul_f32_e32 v124, 0xbfb8aa3b, v124
	v_mul_f32_e32 v129, 0xbfb8aa3b, v129
	v_mul_f32_e32 v125, 0xbfb8aa3b, v125
	v_exp_f32_e32 v126, v126
	v_exp_f32_e32 v122, v122
	v_exp_f32_e32 v127, v127
	v_exp_f32_e32 v123, v123
	v_exp_f32_e32 v128, v128
	v_exp_f32_e32 v124, v124
	v_exp_f32_e32 v129, v129
	v_exp_f32_e32 v125, v125
	v_add_f32_e32 v126, 1.0, v126
	v_add_f32_e32 v122, 1.0, v122
	v_add_f32_e32 v127, 1.0, v127
	v_add_f32_e32 v123, 1.0, v123
	v_add_f32_e32 v128, 1.0, v128
	v_add_f32_e32 v124, 1.0, v124
	v_add_f32_e32 v129, 1.0, v129
	v_add_f32_e32 v125, 1.0, v125
	v_rcp_f32_e32 v126, v126
	v_rcp_f32_e32 v122, v122
	v_rcp_f32_e32 v127, v127
	v_rcp_f32_e32 v123, v123
	v_rcp_f32_e32 v128, v128
	v_rcp_f32_e32 v124, v124
	s_waitcnt vmcnt(1)
	v_lshlrev_b32_e32 v138, 16, v142
	v_and_b32_e32 v139, 0xffff0000, v142
	v_lshlrev_b32_e32 v140, 16, v143
	v_and_b32_e32 v141, 0xffff0000, v143
	v_lshlrev_b32_e32 v142, 16, v144
	v_and_b32_e32 v143, 0xffff0000, v144
	v_lshlrev_b32_e32 v144, 16, v145
	v_and_b32_e32 v145, 0xffff0000, v145
	v_mul_f32_e32 v134, v134, v138
	v_mul_f32_e32 v138, v130, v142
	v_mul_f32_e32 v130, v135, v139
	v_mul_f32_e32 v135, v131, v143
	v_mul_f32_e32 v131, v136, v140
	v_mul_f32_e32 v136, v132, v144
	v_mul_f32_e32 v132, v137, v141
	v_mul_f32_e32 v133, v133, v145
	v_cvt_pk_bf16_f32 v130, v134, v130
	v_cvt_pk_bf16_f32 v131, v131, v132
	v_cvt_pk_bf16_f32 v132, v138, v135
	v_cvt_pk_bf16_f32 v133, v136, v133
	global_load_dwordx4 v[134:137], v[178:179], off
	v_rcp_f32_e32 v129, v129
	v_rcp_f32_e32 v125, v125
	global_store_dwordx4 v[176:177], v[130:133], off offset:256
	v_pk_add_f32 v[120:121], v[120:121], v[64:65]
	v_pk_add_f32 v[118:119], v[118:119], v[62:63]
	v_pk_add_f32 v[116:117], v[116:117], v[60:61]
	v_pk_add_f32 v[114:115], v[114:115], v[58:59]
	v_mul_f32_e32 v118, 0xbfb8aa3b, v118
	v_mul_f32_e32 v114, 0xbfb8aa3b, v114
	v_mul_f32_e32 v119, 0xbfb8aa3b, v119
	v_mul_f32_e32 v115, 0xbfb8aa3b, v115
	v_mul_f32_e32 v120, 0xbfb8aa3b, v120
	v_mul_f32_e32 v116, 0xbfb8aa3b, v116
	v_mul_f32_e32 v121, 0xbfb8aa3b, v121
	v_mul_f32_e32 v117, 0xbfb8aa3b, v117
	v_exp_f32_e32 v118, v118
	v_exp_f32_e32 v114, v114
	v_exp_f32_e32 v119, v119
	v_exp_f32_e32 v115, v115
	v_exp_f32_e32 v120, v120
	v_exp_f32_e32 v116, v116
	v_exp_f32_e32 v121, v121
	v_exp_f32_e32 v117, v117
	v_add_f32_e32 v118, 1.0, v118
	v_add_f32_e32 v114, 1.0, v114
	v_add_f32_e32 v119, 1.0, v119
	v_add_f32_e32 v115, 1.0, v115
	v_add_f32_e32 v120, 1.0, v120
	v_add_f32_e32 v116, 1.0, v116
	v_add_f32_e32 v121, 1.0, v121
	v_add_f32_e32 v117, 1.0, v117
	v_rcp_f32_e32 v118, v118
	v_rcp_f32_e32 v114, v114
	v_rcp_f32_e32 v119, v119
	v_rcp_f32_e32 v115, v115
	v_rcp_f32_e32 v120, v120
	v_rcp_f32_e32 v116, v116
	v_rcp_f32_e32 v121, v121
	v_rcp_f32_e32 v117, v117
	v_pk_add_f32 v[112:113], v[112:113], v[80:81]
	v_pk_add_f32 v[110:111], v[110:111], v[78:79]
	v_pk_add_f32 v[108:109], v[108:109], v[76:77]
	v_pk_add_f32 v[106:107], v[106:107], v[74:75]
	v_mul_f32_e32 v110, 0xbfb8aa3b, v110
	v_mul_f32_e32 v106, 0xbfb8aa3b, v106
	v_mul_f32_e32 v111, 0xbfb8aa3b, v111
	v_mul_f32_e32 v107, 0xbfb8aa3b, v107
	v_mul_f32_e32 v112, 0xbfb8aa3b, v112
	v_mul_f32_e32 v108, 0xbfb8aa3b, v108
	v_mul_f32_e32 v113, 0xbfb8aa3b, v113
	v_mul_f32_e32 v109, 0xbfb8aa3b, v109
	v_exp_f32_e32 v110, v110
	v_exp_f32_e32 v106, v106
	v_exp_f32_e32 v111, v111
	v_exp_f32_e32 v107, v107
	v_exp_f32_e32 v112, v112
	v_exp_f32_e32 v108, v108
	v_exp_f32_e32 v113, v113
	v_exp_f32_e32 v109, v109
	v_add_f32_e32 v110, 1.0, v110
	v_add_f32_e32 v106, 1.0, v106
	v_add_f32_e32 v111, 1.0, v111
	v_add_f32_e32 v107, 1.0, v107
	v_add_f32_e32 v112, 1.0, v112
	v_add_f32_e32 v108, 1.0, v108
	v_add_f32_e32 v113, 1.0, v113
	v_add_f32_e32 v109, 1.0, v109
	v_rcp_f32_e32 v110, v110
	v_rcp_f32_e32 v106, v106
	v_rcp_f32_e32 v111, v111
	v_rcp_f32_e32 v107, v107
	v_rcp_f32_e32 v112, v112
	v_rcp_f32_e32 v108, v108
	v_rcp_f32_e32 v113, v113
	v_rcp_f32_e32 v109, v109
	v_pk_add_f32 v[104:105], v[104:105], v[64:65]
	v_pk_add_f32 v[102:103], v[102:103], v[62:63]
	v_pk_add_f32 v[100:101], v[100:101], v[60:61]
	v_pk_add_f32 v[98:99], v[98:99], v[58:59]
	s_waitcnt vmcnt(1)
	v_lshlrev_b32_e32 v130, 16, v134
	v_and_b32_e32 v131, 0xffff0000, v134
	v_lshlrev_b32_e32 v132, 16, v135
	v_and_b32_e32 v133, 0xffff0000, v135
	v_lshlrev_b32_e32 v134, 16, v136
	v_and_b32_e32 v135, 0xffff0000, v136
	v_lshlrev_b32_e32 v136, 16, v137
	v_and_b32_e32 v137, 0xffff0000, v137
	v_mul_f32_e32 v126, v126, v130
	v_mul_f32_e32 v130, v122, v134
	v_mul_f32_e32 v122, v127, v131
	v_mul_f32_e32 v127, v123, v135
	v_mul_f32_e32 v123, v128, v132
	v_mul_f32_e32 v128, v124, v136
	v_mul_f32_e32 v124, v129, v133
	v_mul_f32_e32 v125, v125, v137
	v_cvt_pk_bf16_f32 v122, v126, v122
	v_cvt_pk_bf16_f32 v123, v123, v124
	v_cvt_pk_bf16_f32 v124, v130, v127
	v_cvt_pk_bf16_f32 v125, v128, v125
	global_load_dwordx4 v[126:129], v[178:179], off offset:256
	v_or_b32_e32 v130, 32, v164
	v_lshlrev_b64 v[132:133], 13, v[172:173]
	v_ashrrev_i32_e32 v131, 31, v130
	v_lshl_add_u64 v[132:133], s[12:13], 0, v[132:133]
	v_lshlrev_b64 v[134:135], 12, v[130:131]
	v_lshl_add_u64 v[132:133], v[132:133], 0, v[162:163]
	v_lshl_add_u64 v[134:135], s[6:7], 0, v[134:135]
	global_store_dwordx4 v[132:133], v[122:125], off
	v_lshl_add_u64 v[134:135], v[134:135], 0, v[162:163]
	v_mul_f32_e32 v102, 0xbfb8aa3b, v102
	v_mul_f32_e32 v98, 0xbfb8aa3b, v98
	v_mul_f32_e32 v103, 0xbfb8aa3b, v103
	v_mul_f32_e32 v99, 0xbfb8aa3b, v99
	v_mul_f32_e32 v104, 0xbfb8aa3b, v104
	v_mul_f32_e32 v100, 0xbfb8aa3b, v100
	v_mul_f32_e32 v105, 0xbfb8aa3b, v105
	v_mul_f32_e32 v101, 0xbfb8aa3b, v101
	v_exp_f32_e32 v102, v102
	v_exp_f32_e32 v98, v98
	v_exp_f32_e32 v103, v103
	v_exp_f32_e32 v99, v99
	v_exp_f32_e32 v104, v104
	v_exp_f32_e32 v100, v100
	v_exp_f32_e32 v105, v105
	v_exp_f32_e32 v101, v101
	v_add_f32_e32 v102, 1.0, v102
	v_add_f32_e32 v98, 1.0, v98
	v_add_f32_e32 v103, 1.0, v103
	v_add_f32_e32 v99, 1.0, v99
	v_add_f32_e32 v104, 1.0, v104
	v_add_f32_e32 v100, 1.0, v100
	v_add_f32_e32 v105, 1.0, v105
	v_add_f32_e32 v101, 1.0, v101
	v_rcp_f32_e32 v102, v102
	v_rcp_f32_e32 v98, v98
	v_rcp_f32_e32 v103, v103
	v_rcp_f32_e32 v99, v99
	v_rcp_f32_e32 v104, v104
	v_rcp_f32_e32 v100, v100
	v_rcp_f32_e32 v105, v105
	v_rcp_f32_e32 v101, v101
	v_pk_add_f32 v[96:97], v[96:97], v[80:81]
	v_pk_add_f32 v[94:95], v[94:95], v[78:79]
	v_pk_add_f32 v[92:93], v[92:93], v[76:77]
	v_pk_add_f32 v[90:91], v[90:91], v[74:75]
	v_mul_f32_e32 v94, 0xbfb8aa3b, v94
	v_mul_f32_e32 v90, 0xbfb8aa3b, v90
	v_mul_f32_e32 v95, 0xbfb8aa3b, v95
	v_mul_f32_e32 v91, 0xbfb8aa3b, v91
	v_mul_f32_e32 v96, 0xbfb8aa3b, v96
	v_mul_f32_e32 v92, 0xbfb8aa3b, v92
	v_mul_f32_e32 v97, 0xbfb8aa3b, v97
	v_mul_f32_e32 v93, 0xbfb8aa3b, v93
	v_exp_f32_e32 v94, v94
	v_exp_f32_e32 v90, v90
	v_exp_f32_e32 v95, v95
	v_exp_f32_e32 v91, v91
	v_exp_f32_e32 v96, v96
	v_exp_f32_e32 v92, v92
	v_exp_f32_e32 v97, v97
	v_exp_f32_e32 v93, v93
	v_add_f32_e32 v94, 1.0, v94
	v_add_f32_e32 v90, 1.0, v90
	v_add_f32_e32 v95, 1.0, v95
	v_add_f32_e32 v91, 1.0, v91
	v_add_f32_e32 v96, 1.0, v96
	v_add_f32_e32 v92, 1.0, v92
	v_add_f32_e32 v97, 1.0, v97
	v_add_f32_e32 v93, 1.0, v93
	v_rcp_f32_e32 v94, v94
	v_rcp_f32_e32 v90, v90
	v_rcp_f32_e32 v95, v95
	v_rcp_f32_e32 v91, v91
	v_rcp_f32_e32 v96, v96
	v_rcp_f32_e32 v92, v92
	v_rcp_f32_e32 v97, v97
	v_rcp_f32_e32 v93, v93
	v_pk_add_f32 v[88:89], v[88:89], v[64:65]
	v_pk_add_f32 v[86:87], v[86:87], v[62:63]
	s_waitcnt vmcnt(1)
	v_lshlrev_b32_e32 v122, 16, v126
	v_and_b32_e32 v123, 0xffff0000, v126
	v_lshlrev_b32_e32 v124, 16, v127
	v_and_b32_e32 v125, 0xffff0000, v127
	v_lshlrev_b32_e32 v126, 16, v128
	v_and_b32_e32 v127, 0xffff0000, v128
	v_lshlrev_b32_e32 v128, 16, v129
	v_and_b32_e32 v129, 0xffff0000, v129
	v_mul_f32_e32 v118, v118, v122
	v_mul_f32_e32 v122, v114, v126
	v_mul_f32_e32 v114, v119, v123
	v_mul_f32_e32 v119, v115, v127
	v_mul_f32_e32 v115, v120, v124
	v_mul_f32_e32 v120, v116, v128
	v_mul_f32_e32 v116, v121, v125
	v_mul_f32_e32 v117, v117, v129
	v_cvt_pk_bf16_f32 v114, v118, v114
	v_cvt_pk_bf16_f32 v115, v115, v116
	v_cvt_pk_bf16_f32 v116, v122, v119
	v_cvt_pk_bf16_f32 v117, v120, v117
	global_load_dwordx4 v[118:121], v[134:135], off
	v_pk_add_f32 v[84:85], v[84:85], v[60:61]
	global_store_dwordx4 v[132:133], v[114:117], off offset:256
	v_pk_add_f32 v[82:83], v[82:83], v[58:59]
	v_mul_f32_e32 v86, 0xbfb8aa3b, v86
	v_mul_f32_e32 v82, 0xbfb8aa3b, v82
	v_mul_f32_e32 v87, 0xbfb8aa3b, v87
	v_mul_f32_e32 v83, 0xbfb8aa3b, v83
	v_mul_f32_e32 v88, 0xbfb8aa3b, v88
	v_mul_f32_e32 v84, 0xbfb8aa3b, v84
	v_mul_f32_e32 v89, 0xbfb8aa3b, v89
	v_mul_f32_e32 v85, 0xbfb8aa3b, v85
	v_exp_f32_e32 v86, v86
	v_exp_f32_e32 v82, v82
	v_exp_f32_e32 v87, v87
	v_exp_f32_e32 v83, v83
	v_exp_f32_e32 v88, v88
	v_exp_f32_e32 v84, v84
	v_exp_f32_e32 v89, v89
	v_exp_f32_e32 v85, v85
	v_add_f32_e32 v86, 1.0, v86
	v_add_f32_e32 v82, 1.0, v82
	v_add_f32_e32 v87, 1.0, v87
	v_add_f32_e32 v83, 1.0, v83
	v_add_f32_e32 v88, 1.0, v88
	v_add_f32_e32 v84, 1.0, v84
	v_add_f32_e32 v89, 1.0, v89
	v_add_f32_e32 v85, 1.0, v85
	v_rcp_f32_e32 v86, v86
	v_rcp_f32_e32 v82, v82
	v_rcp_f32_e32 v87, v87
	v_rcp_f32_e32 v83, v83
	v_rcp_f32_e32 v88, v88
	v_rcp_f32_e32 v84, v84
	v_rcp_f32_e32 v89, v89
	v_rcp_f32_e32 v85, v85
	v_pk_add_f32 v[72:73], v[72:73], v[80:81]
	v_pk_add_f32 v[70:71], v[70:71], v[78:79]
	v_pk_add_f32 v[68:69], v[68:69], v[76:77]
	v_pk_add_f32 v[66:67], v[66:67], v[74:75]
	v_mul_f32_e32 v70, 0xbfb8aa3b, v70
	v_mul_f32_e32 v66, 0xbfb8aa3b, v66
	v_mul_f32_e32 v71, 0xbfb8aa3b, v71
	v_mul_f32_e32 v67, 0xbfb8aa3b, v67
	v_mul_f32_e32 v72, 0xbfb8aa3b, v72
	v_mul_f32_e32 v68, 0xbfb8aa3b, v68
	v_mul_f32_e32 v73, 0xbfb8aa3b, v73
	v_mul_f32_e32 v69, 0xbfb8aa3b, v69
	v_exp_f32_e32 v70, v70
	v_exp_f32_e32 v66, v66
	v_exp_f32_e32 v71, v71
	v_exp_f32_e32 v67, v67
	v_exp_f32_e32 v72, v72
	v_exp_f32_e32 v68, v68
	v_exp_f32_e32 v73, v73
	v_exp_f32_e32 v69, v69
	v_add_f32_e32 v70, 1.0, v70
	v_add_f32_e32 v66, 1.0, v66
	v_add_f32_e32 v71, 1.0, v71
	v_add_f32_e32 v67, 1.0, v67
	v_add_f32_e32 v72, 1.0, v72
	v_add_f32_e32 v68, 1.0, v68
	v_add_f32_e32 v73, 1.0, v73
	v_add_f32_e32 v69, 1.0, v69
	v_rcp_f32_e32 v70, v70
	v_rcp_f32_e32 v66, v66
	v_rcp_f32_e32 v71, v71
	v_rcp_f32_e32 v67, v67
	v_rcp_f32_e32 v72, v72
	v_rcp_f32_e32 v68, v68
	v_rcp_f32_e32 v73, v73
	v_rcp_f32_e32 v69, v69
	v_pk_add_f32 v[56:57], v[56:57], v[64:65]
	v_pk_add_f32 v[54:55], v[54:55], v[62:63]
	v_pk_add_f32 v[52:53], v[52:53], v[60:61]
	v_pk_add_f32 v[50:51], v[50:51], v[58:59]
	v_mul_f32_e32 v54, 0xbfb8aa3b, v54
	v_mul_f32_e32 v50, 0xbfb8aa3b, v50
	v_mul_f32_e32 v55, 0xbfb8aa3b, v55
	v_mul_f32_e32 v51, 0xbfb8aa3b, v51
	s_waitcnt vmcnt(1)
	v_lshlrev_b32_e32 v114, 16, v118
	v_and_b32_e32 v115, 0xffff0000, v118
	v_lshlrev_b32_e32 v116, 16, v119
	v_and_b32_e32 v117, 0xffff0000, v119
	v_lshlrev_b32_e32 v118, 16, v120
	v_and_b32_e32 v119, 0xffff0000, v120
	v_lshlrev_b32_e32 v120, 16, v121
	v_and_b32_e32 v121, 0xffff0000, v121
	v_mul_f32_e32 v110, v110, v114
	v_mul_f32_e32 v114, v106, v118
	v_mul_f32_e32 v106, v111, v115
	v_mul_f32_e32 v111, v107, v119
	v_mul_f32_e32 v107, v112, v116
	v_mul_f32_e32 v112, v108, v120
	v_mul_f32_e32 v108, v113, v117
	v_mul_f32_e32 v109, v109, v121
	v_cvt_pk_bf16_f32 v106, v110, v106
	v_cvt_pk_bf16_f32 v107, v107, v108
	v_cvt_pk_bf16_f32 v108, v114, v111
	v_cvt_pk_bf16_f32 v109, v112, v109
	global_load_dwordx4 v[110:113], v[134:135], off offset:256
	v_or_b32_e32 v114, 48, v164
	v_lshlrev_b64 v[116:117], 13, v[130:131]
	v_ashrrev_i32_e32 v115, 31, v114
	v_lshl_add_u64 v[116:117], s[12:13], 0, v[116:117]
	v_lshlrev_b64 v[118:119], 12, v[114:115]
	v_lshl_add_u64 v[116:117], v[116:117], 0, v[162:163]
	v_lshl_add_u64 v[118:119], s[6:7], 0, v[118:119]
	global_store_dwordx4 v[116:117], v[106:109], off
	v_lshl_add_u64 v[118:119], v[118:119], 0, v[162:163]
	v_mul_f32_e32 v56, 0xbfb8aa3b, v56
	v_mul_f32_e32 v52, 0xbfb8aa3b, v52
	v_mul_f32_e32 v57, 0xbfb8aa3b, v57
	v_mul_f32_e32 v53, 0xbfb8aa3b, v53
	v_exp_f32_e32 v54, v54
	v_exp_f32_e32 v50, v50
	v_exp_f32_e32 v55, v55
	v_exp_f32_e32 v51, v51
	v_exp_f32_e32 v56, v56
	v_exp_f32_e32 v52, v52
	v_exp_f32_e32 v57, v57
	v_exp_f32_e32 v53, v53
	v_add_f32_e32 v54, 1.0, v54
	v_add_f32_e32 v50, 1.0, v50
	v_add_f32_e32 v55, 1.0, v55
	v_add_f32_e32 v51, 1.0, v51
	v_add_f32_e32 v56, 1.0, v56
	v_add_f32_e32 v52, 1.0, v52
	v_add_f32_e32 v57, 1.0, v57
	v_add_f32_e32 v53, 1.0, v53
	v_rcp_f32_e32 v54, v54
	v_rcp_f32_e32 v50, v50
	v_rcp_f32_e32 v55, v55
	v_rcp_f32_e32 v51, v51
	v_rcp_f32_e32 v56, v56
	v_rcp_f32_e32 v52, v52
	v_rcp_f32_e32 v57, v57
	v_rcp_f32_e32 v53, v53
	v_pk_add_f32 v[48:49], v[48:49], v[80:81]
	v_pk_add_f32 v[46:47], v[46:47], v[78:79]
	v_pk_add_f32 v[44:45], v[44:45], v[76:77]
	v_pk_add_f32 v[42:43], v[42:43], v[74:75]
	v_mul_f32_e32 v46, 0xbfb8aa3b, v46
	v_mul_f32_e32 v42, 0xbfb8aa3b, v42
	v_mul_f32_e32 v47, 0xbfb8aa3b, v47
	v_mul_f32_e32 v43, 0xbfb8aa3b, v43
	v_mul_f32_e32 v48, 0xbfb8aa3b, v48
	v_mul_f32_e32 v44, 0xbfb8aa3b, v44
	v_mul_f32_e32 v49, 0xbfb8aa3b, v49
	v_mul_f32_e32 v45, 0xbfb8aa3b, v45
	v_exp_f32_e32 v46, v46
	v_exp_f32_e32 v42, v42
	v_exp_f32_e32 v47, v47
	v_exp_f32_e32 v43, v43
	v_exp_f32_e32 v48, v48
	v_exp_f32_e32 v44, v44
	v_exp_f32_e32 v49, v49
	v_exp_f32_e32 v45, v45
	v_add_f32_e32 v46, 1.0, v46
	v_add_f32_e32 v42, 1.0, v42
	v_add_f32_e32 v47, 1.0, v47
	v_add_f32_e32 v43, 1.0, v43
	v_add_f32_e32 v48, 1.0, v48
	v_add_f32_e32 v44, 1.0, v44
	v_add_f32_e32 v49, 1.0, v49
	v_add_f32_e32 v45, 1.0, v45
	v_rcp_f32_e32 v46, v46
	v_rcp_f32_e32 v42, v42
	v_rcp_f32_e32 v47, v47
	v_rcp_f32_e32 v43, v43
	v_rcp_f32_e32 v48, v48
	v_rcp_f32_e32 v44, v44
	v_rcp_f32_e32 v49, v49
	v_rcp_f32_e32 v45, v45
	v_pk_add_f32 v[40:41], v[40:41], v[64:65]
	v_pk_add_f32 v[38:39], v[38:39], v[62:63]
	v_pk_add_f32 v[36:37], v[36:37], v[60:61]
	v_pk_add_f32 v[34:35], v[34:35], v[58:59]
	v_mul_f32_e32 v38, 0xbfb8aa3b, v38
	v_mul_f32_e32 v34, 0xbfb8aa3b, v34
	s_waitcnt vmcnt(1)
	v_lshlrev_b32_e32 v106, 16, v110
	v_and_b32_e32 v107, 0xffff0000, v110
	v_lshlrev_b32_e32 v108, 16, v111
	v_and_b32_e32 v109, 0xffff0000, v111
	v_lshlrev_b32_e32 v110, 16, v112
	v_and_b32_e32 v111, 0xffff0000, v112
	v_lshlrev_b32_e32 v112, 16, v113
	v_and_b32_e32 v113, 0xffff0000, v113
	v_mul_f32_e32 v102, v102, v106
	v_mul_f32_e32 v106, v98, v110
	v_mul_f32_e32 v98, v103, v107
	v_mul_f32_e32 v103, v99, v111
	v_mul_f32_e32 v99, v104, v108
	v_mul_f32_e32 v104, v100, v112
	v_mul_f32_e32 v100, v105, v109
	v_mul_f32_e32 v101, v101, v113
	v_cvt_pk_bf16_f32 v98, v102, v98
	v_cvt_pk_bf16_f32 v99, v99, v100
	v_cvt_pk_bf16_f32 v100, v106, v103
	v_cvt_pk_bf16_f32 v101, v104, v101
	global_load_dwordx4 v[102:105], v[118:119], off
	v_mul_f32_e32 v39, 0xbfb8aa3b, v39
	global_store_dwordx4 v[116:117], v[98:101], off offset:256
	v_mul_f32_e32 v35, 0xbfb8aa3b, v35
	v_mul_f32_e32 v40, 0xbfb8aa3b, v40
	v_mul_f32_e32 v36, 0xbfb8aa3b, v36
	v_mul_f32_e32 v41, 0xbfb8aa3b, v41
	v_mul_f32_e32 v37, 0xbfb8aa3b, v37
	v_exp_f32_e32 v38, v38
	v_exp_f32_e32 v34, v34
	v_exp_f32_e32 v39, v39
	v_exp_f32_e32 v35, v35
	v_exp_f32_e32 v40, v40
	v_exp_f32_e32 v36, v36
	v_exp_f32_e32 v41, v41
	v_exp_f32_e32 v37, v37
	v_add_f32_e32 v38, 1.0, v38
	v_add_f32_e32 v34, 1.0, v34
	v_add_f32_e32 v39, 1.0, v39
	v_add_f32_e32 v35, 1.0, v35
	v_add_f32_e32 v40, 1.0, v40
	v_add_f32_e32 v36, 1.0, v36
	v_add_f32_e32 v41, 1.0, v41
	v_add_f32_e32 v37, 1.0, v37
	v_rcp_f32_e32 v38, v38
	v_rcp_f32_e32 v34, v34
	v_rcp_f32_e32 v39, v39
	v_rcp_f32_e32 v35, v35
	v_rcp_f32_e32 v40, v40
	v_rcp_f32_e32 v36, v36
	v_rcp_f32_e32 v41, v41
	v_rcp_f32_e32 v37, v37
	v_pk_add_f32 v[32:33], v[32:33], v[80:81]
	v_pk_add_f32 v[30:31], v[30:31], v[78:79]
	v_pk_add_f32 v[28:29], v[28:29], v[76:77]
	v_pk_add_f32 v[26:27], v[26:27], v[74:75]
	v_mul_f32_e32 v30, 0xbfb8aa3b, v30
	v_mul_f32_e32 v26, 0xbfb8aa3b, v26
	v_mul_f32_e32 v31, 0xbfb8aa3b, v31
	v_mul_f32_e32 v27, 0xbfb8aa3b, v27
	v_mul_f32_e32 v32, 0xbfb8aa3b, v32
	v_mul_f32_e32 v28, 0xbfb8aa3b, v28
	v_mul_f32_e32 v33, 0xbfb8aa3b, v33
	v_mul_f32_e32 v29, 0xbfb8aa3b, v29
	v_exp_f32_e32 v30, v30
	v_exp_f32_e32 v26, v26
	v_exp_f32_e32 v31, v31
	v_exp_f32_e32 v27, v27
	v_exp_f32_e32 v32, v32
	v_exp_f32_e32 v28, v28
	v_exp_f32_e32 v33, v33
	v_exp_f32_e32 v29, v29
	v_add_f32_e32 v30, 1.0, v30
	v_add_f32_e32 v26, 1.0, v26
	v_add_f32_e32 v31, 1.0, v31
	v_add_f32_e32 v27, 1.0, v27
	v_add_f32_e32 v32, 1.0, v32
	v_add_f32_e32 v28, 1.0, v28
	v_add_f32_e32 v33, 1.0, v33
	v_add_f32_e32 v29, 1.0, v29
	v_rcp_f32_e32 v30, v30
	v_rcp_f32_e32 v26, v26
	v_rcp_f32_e32 v31, v31
	v_rcp_f32_e32 v27, v27
	v_rcp_f32_e32 v32, v32
	v_rcp_f32_e32 v28, v28
	v_rcp_f32_e32 v33, v33
	v_rcp_f32_e32 v29, v29
	v_pk_add_f32 v[24:25], v[24:25], v[64:65]
	v_pk_add_f32 v[22:23], v[22:23], v[62:63]
	v_pk_add_f32 v[20:21], v[20:21], v[60:61]
	v_pk_add_f32 v[18:19], v[18:19], v[58:59]
	v_mul_f32_e32 v22, 0xbfb8aa3b, v22
	v_mul_f32_e32 v18, 0xbfb8aa3b, v18
	v_mul_f32_e32 v23, 0xbfb8aa3b, v23
	v_mul_f32_e32 v19, 0xbfb8aa3b, v19
	v_mul_f32_e32 v24, 0xbfb8aa3b, v24
	v_mul_f32_e32 v20, 0xbfb8aa3b, v20
	v_mul_f32_e32 v25, 0xbfb8aa3b, v25
	v_mul_f32_e32 v21, 0xbfb8aa3b, v21
	s_waitcnt vmcnt(1)
	v_lshlrev_b32_e32 v98, 16, v102
	v_and_b32_e32 v99, 0xffff0000, v102
	v_lshlrev_b32_e32 v100, 16, v103
	v_and_b32_e32 v101, 0xffff0000, v103
	v_lshlrev_b32_e32 v102, 16, v104
	v_and_b32_e32 v103, 0xffff0000, v104
	v_lshlrev_b32_e32 v104, 16, v105
	v_and_b32_e32 v105, 0xffff0000, v105
	v_mul_f32_e32 v94, v94, v98
	v_mul_f32_e32 v98, v90, v102
	v_mul_f32_e32 v90, v95, v99
	v_mul_f32_e32 v95, v91, v103
	v_mul_f32_e32 v91, v96, v100
	v_mul_f32_e32 v96, v92, v104
	v_mul_f32_e32 v92, v97, v101
	v_mul_f32_e32 v93, v93, v105
	v_cvt_pk_bf16_f32 v90, v94, v90
	v_cvt_pk_bf16_f32 v91, v91, v92
	v_cvt_pk_bf16_f32 v92, v98, v95
	v_cvt_pk_bf16_f32 v93, v96, v93
	global_load_dwordx4 v[94:97], v[118:119], off offset:256
	v_add_u32_e32 v98, 0x80, v164
	v_lshlrev_b64 v[100:101], 13, v[114:115]
	v_ashrrev_i32_e32 v99, 31, v98
	v_lshl_add_u64 v[100:101], s[12:13], 0, v[100:101]
	v_lshlrev_b64 v[102:103], 12, v[98:99]
	v_lshl_add_u64 v[100:101], v[100:101], 0, v[162:163]
	v_lshl_add_u64 v[102:103], s[6:7], 0, v[102:103]
	global_store_dwordx4 v[100:101], v[90:93], off
	v_lshl_add_u64 v[102:103], v[102:103], 0, v[162:163]
	v_exp_f32_e32 v22, v22
	v_exp_f32_e32 v18, v18
	v_exp_f32_e32 v23, v23
	v_exp_f32_e32 v19, v19
	v_exp_f32_e32 v24, v24
	v_exp_f32_e32 v20, v20
	v_exp_f32_e32 v25, v25
	v_exp_f32_e32 v21, v21
	v_add_f32_e32 v22, 1.0, v22
	v_add_f32_e32 v18, 1.0, v18
	v_add_f32_e32 v23, 1.0, v23
	v_add_f32_e32 v19, 1.0, v19
	v_add_f32_e32 v24, 1.0, v24
	v_add_f32_e32 v20, 1.0, v20
	v_add_f32_e32 v25, 1.0, v25
	v_add_f32_e32 v21, 1.0, v21
	v_rcp_f32_e32 v22, v22
	v_rcp_f32_e32 v18, v18
	v_rcp_f32_e32 v23, v23
	v_rcp_f32_e32 v19, v19
	v_rcp_f32_e32 v24, v24
	v_rcp_f32_e32 v20, v20
	v_rcp_f32_e32 v25, v25
	v_rcp_f32_e32 v21, v21
	v_pk_add_f32 v[16:17], v[16:17], v[80:81]
	v_pk_add_f32 v[14:15], v[14:15], v[78:79]
	v_pk_add_f32 v[12:13], v[12:13], v[76:77]
	v_pk_add_f32 v[10:11], v[10:11], v[74:75]
	v_mul_f32_e32 v14, 0xbfb8aa3b, v14
	v_mul_f32_e32 v10, 0xbfb8aa3b, v10
	v_mul_f32_e32 v15, 0xbfb8aa3b, v15
	v_mul_f32_e32 v11, 0xbfb8aa3b, v11
	v_mul_f32_e32 v16, 0xbfb8aa3b, v16
	v_mul_f32_e32 v12, 0xbfb8aa3b, v12
	v_mul_f32_e32 v17, 0xbfb8aa3b, v17
	v_mul_f32_e32 v13, 0xbfb8aa3b, v13
	v_exp_f32_e32 v14, v14
	v_exp_f32_e32 v10, v10
	v_exp_f32_e32 v15, v15
	v_exp_f32_e32 v11, v11
	v_exp_f32_e32 v16, v16
	v_exp_f32_e32 v12, v12
	v_exp_f32_e32 v17, v17
	v_exp_f32_e32 v13, v13
	v_add_f32_e32 v14, 1.0, v14
	v_add_f32_e32 v10, 1.0, v10
	v_add_f32_e32 v15, 1.0, v15
	v_add_f32_e32 v11, 1.0, v11
	v_add_f32_e32 v16, 1.0, v16
	v_add_f32_e32 v12, 1.0, v12
	v_add_f32_e32 v17, 1.0, v17
	v_add_f32_e32 v13, 1.0, v13
	v_rcp_f32_e32 v14, v14
	v_rcp_f32_e32 v10, v10
	v_rcp_f32_e32 v15, v15
	v_rcp_f32_e32 v11, v11
	v_rcp_f32_e32 v16, v16
	v_rcp_f32_e32 v12, v12
	v_rcp_f32_e32 v17, v17
	v_rcp_f32_e32 v13, v13
	v_pk_add_f32 v[8:9], v[8:9], v[64:65]
	v_pk_add_f32 v[6:7], v[6:7], v[62:63]
	v_pk_add_f32 v[4:5], v[4:5], v[60:61]
	v_pk_add_f32 v[2:3], v[2:3], v[58:59]
	v_mul_f32_e32 v6, 0xbfb8aa3b, v6
	v_mul_f32_e32 v2, 0xbfb8aa3b, v2
	v_mul_f32_e32 v7, 0xbfb8aa3b, v7
	v_mul_f32_e32 v3, 0xbfb8aa3b, v3
	v_mul_f32_e32 v8, 0xbfb8aa3b, v8
	v_mul_f32_e32 v4, 0xbfb8aa3b, v4
	s_waitcnt vmcnt(1)
	v_lshlrev_b32_e32 v90, 16, v94
	v_and_b32_e32 v91, 0xffff0000, v94
	v_lshlrev_b32_e32 v92, 16, v95
	v_and_b32_e32 v93, 0xffff0000, v95
	v_lshlrev_b32_e32 v94, 16, v96
	v_and_b32_e32 v95, 0xffff0000, v96
	v_lshlrev_b32_e32 v96, 16, v97
	v_and_b32_e32 v97, 0xffff0000, v97
	v_mul_f32_e32 v86, v86, v90
	v_mul_f32_e32 v90, v82, v94
	v_mul_f32_e32 v82, v87, v91
	v_mul_f32_e32 v87, v83, v95
	v_mul_f32_e32 v83, v88, v92
	v_mul_f32_e32 v88, v84, v96
	v_mul_f32_e32 v84, v89, v93
	v_mul_f32_e32 v85, v85, v97
	v_cvt_pk_bf16_f32 v82, v86, v82
	v_cvt_pk_bf16_f32 v83, v83, v84
	v_cvt_pk_bf16_f32 v84, v90, v87
	v_cvt_pk_bf16_f32 v85, v88, v85
	global_load_dwordx4 v[86:89], v[102:103], off
	v_mul_f32_e32 v9, 0xbfb8aa3b, v9
	global_store_dwordx4 v[100:101], v[82:85], off offset:256
	v_mul_f32_e32 v5, 0xbfb8aa3b, v5
	v_exp_f32_e32 v6, v6
	v_exp_f32_e32 v2, v2
	v_exp_f32_e32 v7, v7
	v_exp_f32_e32 v3, v3
	v_exp_f32_e32 v8, v8
	v_exp_f32_e32 v4, v4
	v_exp_f32_e32 v9, v9
	v_exp_f32_e32 v5, v5
	v_add_f32_e32 v6, 1.0, v6
	v_add_f32_e32 v2, 1.0, v2
	v_add_f32_e32 v7, 1.0, v7
	v_add_f32_e32 v3, 1.0, v3
	v_add_f32_e32 v8, 1.0, v8
	v_add_f32_e32 v4, 1.0, v4
	v_add_f32_e32 v9, 1.0, v9
	v_add_f32_e32 v5, 1.0, v5
	v_rcp_f32_e32 v6, v6
	v_rcp_f32_e32 v2, v2
	v_rcp_f32_e32 v7, v7
	v_rcp_f32_e32 v3, v3
	v_rcp_f32_e32 v8, v8
	v_rcp_f32_e32 v4, v4
	v_rcp_f32_e32 v9, v9
	v_rcp_f32_e32 v5, v5
	s_waitcnt vmcnt(1)
	v_lshlrev_b32_e32 v82, 16, v86
	v_and_b32_e32 v83, 0xffff0000, v86
	v_lshlrev_b32_e32 v84, 16, v87
	v_and_b32_e32 v85, 0xffff0000, v87
	v_lshlrev_b32_e32 v86, 16, v88
	v_and_b32_e32 v87, 0xffff0000, v88
	v_lshlrev_b32_e32 v88, 16, v89
	v_and_b32_e32 v89, 0xffff0000, v89
	v_mul_f32_e32 v70, v70, v82
	v_mul_f32_e32 v82, v66, v86
	v_mul_f32_e32 v66, v71, v83
	v_mul_f32_e32 v71, v67, v87
	v_mul_f32_e32 v67, v72, v84
	v_mul_f32_e32 v72, v68, v88
	v_mul_f32_e32 v68, v73, v85
	v_mul_f32_e32 v69, v69, v89
	v_cvt_pk_bf16_f32 v66, v70, v66
	v_cvt_pk_bf16_f32 v67, v67, v68
	v_cvt_pk_bf16_f32 v68, v82, v71
	v_cvt_pk_bf16_f32 v69, v72, v69
	global_load_dwordx4 v[70:73], v[102:103], off offset:256
	v_add_u32_e32 v82, 0x90, v164
	v_lshlrev_b64 v[84:85], 13, v[98:99]
	v_ashrrev_i32_e32 v83, 31, v82
	v_lshl_add_u64 v[84:85], s[12:13], 0, v[84:85]
	v_lshlrev_b64 v[86:87], 12, v[82:83]
	v_lshl_add_u64 v[84:85], v[84:85], 0, v[162:163]
	v_lshl_add_u64 v[86:87], s[6:7], 0, v[86:87]
	global_store_dwordx4 v[84:85], v[66:69], off
	v_lshl_add_u64 v[86:87], v[86:87], 0, v[162:163]
	s_waitcnt vmcnt(1)
	v_lshlrev_b32_e32 v66, 16, v70
	v_and_b32_e32 v67, 0xffff0000, v70
	v_lshlrev_b32_e32 v68, 16, v71
	v_and_b32_e32 v69, 0xffff0000, v71
	v_lshlrev_b32_e32 v70, 16, v72
	v_and_b32_e32 v71, 0xffff0000, v72
	v_lshlrev_b32_e32 v72, 16, v73
	v_and_b32_e32 v73, 0xffff0000, v73
	v_mul_f32_e32 v54, v54, v66
	v_mul_f32_e32 v66, v50, v70
	v_mul_f32_e32 v50, v55, v67
	v_mul_f32_e32 v55, v51, v71
	v_mul_f32_e32 v51, v56, v68
	v_mul_f32_e32 v56, v52, v72
	v_mul_f32_e32 v52, v57, v69
	v_mul_f32_e32 v53, v53, v73
	v_cvt_pk_bf16_f32 v50, v54, v50
	v_cvt_pk_bf16_f32 v51, v51, v52
	v_cvt_pk_bf16_f32 v52, v66, v55
	v_cvt_pk_bf16_f32 v53, v56, v53
	global_load_dwordx4 v[54:57], v[86:87], off
	s_nop 0
	global_store_dwordx4 v[84:85], v[50:53], off offset:256
	s_waitcnt vmcnt(1)
	s_nop 0
	v_lshlrev_b32_e32 v50, 16, v54
	v_and_b32_e32 v51, 0xffff0000, v54
	v_lshlrev_b32_e32 v52, 16, v55
	v_and_b32_e32 v53, 0xffff0000, v55
	v_lshlrev_b32_e32 v54, 16, v56
	v_and_b32_e32 v55, 0xffff0000, v56
	v_lshlrev_b32_e32 v56, 16, v57
	v_and_b32_e32 v57, 0xffff0000, v57
	v_mul_f32_e32 v46, v46, v50
	v_mul_f32_e32 v50, v42, v54
	v_mul_f32_e32 v42, v47, v51
	v_mul_f32_e32 v47, v43, v55
	v_mul_f32_e32 v43, v48, v52
	v_mul_f32_e32 v48, v44, v56
	v_mul_f32_e32 v44, v49, v53
	v_mul_f32_e32 v45, v45, v57
	v_cvt_pk_bf16_f32 v42, v46, v42
	v_cvt_pk_bf16_f32 v43, v43, v44
	v_cvt_pk_bf16_f32 v44, v50, v47
	v_cvt_pk_bf16_f32 v45, v48, v45
	global_load_dwordx4 v[46:49], v[86:87], off offset:256
	v_add_u32_e32 v50, 0xa0, v164
	v_lshlrev_b64 v[52:53], 13, v[82:83]
	v_ashrrev_i32_e32 v51, 31, v50
	v_lshl_add_u64 v[52:53], s[12:13], 0, v[52:53]
	v_lshlrev_b64 v[54:55], 12, v[50:51]
	v_lshl_add_u64 v[52:53], v[52:53], 0, v[162:163]
	v_lshl_add_u64 v[54:55], s[6:7], 0, v[54:55]
	global_store_dwordx4 v[52:53], v[42:45], off
	v_lshl_add_u64 v[54:55], v[54:55], 0, v[162:163]
	s_waitcnt vmcnt(1)
	v_lshlrev_b32_e32 v42, 16, v46
	v_and_b32_e32 v43, 0xffff0000, v46
	v_lshlrev_b32_e32 v44, 16, v47
	v_and_b32_e32 v45, 0xffff0000, v47
	v_lshlrev_b32_e32 v46, 16, v48
	v_and_b32_e32 v47, 0xffff0000, v48
	v_lshlrev_b32_e32 v48, 16, v49
	v_and_b32_e32 v49, 0xffff0000, v49
	v_mul_f32_e32 v38, v38, v42
	v_mul_f32_e32 v42, v34, v46
	v_mul_f32_e32 v34, v39, v43
	v_mul_f32_e32 v39, v35, v47
	v_mul_f32_e32 v35, v40, v44
	v_mul_f32_e32 v40, v36, v48
	v_mul_f32_e32 v36, v41, v45
	v_mul_f32_e32 v37, v37, v49
	v_cvt_pk_bf16_f32 v34, v38, v34
	v_cvt_pk_bf16_f32 v35, v35, v36
	v_cvt_pk_bf16_f32 v36, v42, v39
	v_cvt_pk_bf16_f32 v37, v40, v37
	global_load_dwordx4 v[38:41], v[54:55], off
	s_nop 0
	global_store_dwordx4 v[52:53], v[34:37], off offset:256
	s_waitcnt vmcnt(1)
	s_nop 0
	v_lshlrev_b32_e32 v34, 16, v38
	v_and_b32_e32 v35, 0xffff0000, v38
	v_lshlrev_b32_e32 v36, 16, v39
	v_and_b32_e32 v37, 0xffff0000, v39
	v_lshlrev_b32_e32 v38, 16, v40
	v_and_b32_e32 v39, 0xffff0000, v40
	v_lshlrev_b32_e32 v40, 16, v41
	v_and_b32_e32 v41, 0xffff0000, v41
	v_mul_f32_e32 v30, v30, v34
	v_mul_f32_e32 v34, v26, v38
	v_mul_f32_e32 v26, v31, v35
	v_mul_f32_e32 v31, v27, v39
	v_mul_f32_e32 v27, v32, v36
	v_mul_f32_e32 v32, v28, v40
	v_mul_f32_e32 v28, v33, v37
	v_mul_f32_e32 v29, v29, v41
	v_cvt_pk_bf16_f32 v26, v30, v26
	v_cvt_pk_bf16_f32 v27, v27, v28
	v_cvt_pk_bf16_f32 v28, v34, v31
	v_cvt_pk_bf16_f32 v29, v32, v29
	global_load_dwordx4 v[30:33], v[54:55], off offset:256
	v_add_u32_e32 v34, 0xb0, v164
	v_lshlrev_b64 v[36:37], 13, v[50:51]
	v_ashrrev_i32_e32 v35, 31, v34
	v_lshl_add_u64 v[36:37], s[12:13], 0, v[36:37]
	v_lshlrev_b64 v[38:39], 12, v[34:35]
	v_lshl_add_u64 v[36:37], v[36:37], 0, v[162:163]
	v_lshl_add_u64 v[38:39], s[6:7], 0, v[38:39]
	global_store_dwordx4 v[36:37], v[26:29], off
	v_lshl_add_u64 v[38:39], v[38:39], 0, v[162:163]
	s_waitcnt vmcnt(1)
	v_lshlrev_b32_e32 v26, 16, v30
	v_and_b32_e32 v27, 0xffff0000, v30
	v_lshlrev_b32_e32 v28, 16, v31
	v_and_b32_e32 v29, 0xffff0000, v31
	v_lshlrev_b32_e32 v30, 16, v32
	v_and_b32_e32 v31, 0xffff0000, v32
	v_lshlrev_b32_e32 v32, 16, v33
	v_and_b32_e32 v33, 0xffff0000, v33
	v_mul_f32_e32 v22, v22, v26
	v_mul_f32_e32 v26, v18, v30
	v_mul_f32_e32 v18, v23, v27
	v_mul_f32_e32 v23, v19, v31
	v_mul_f32_e32 v19, v24, v28
	v_mul_f32_e32 v24, v20, v32
	v_mul_f32_e32 v20, v25, v29
	v_mul_f32_e32 v21, v21, v33
	v_cvt_pk_bf16_f32 v18, v22, v18
	v_cvt_pk_bf16_f32 v19, v19, v20
	v_cvt_pk_bf16_f32 v20, v26, v23
	v_cvt_pk_bf16_f32 v21, v24, v21
	global_load_dwordx4 v[22:25], v[38:39], off
	s_nop 0
	global_store_dwordx4 v[36:37], v[18:21], off offset:256
	s_waitcnt vmcnt(1)
	s_nop 0
	v_lshlrev_b32_e32 v18, 16, v22
	v_and_b32_e32 v19, 0xffff0000, v22
	v_lshlrev_b32_e32 v20, 16, v23
	v_and_b32_e32 v21, 0xffff0000, v23
	v_lshlrev_b32_e32 v22, 16, v24
	v_and_b32_e32 v23, 0xffff0000, v24
	v_lshlrev_b32_e32 v24, 16, v25
	v_and_b32_e32 v25, 0xffff0000, v25
	v_mul_f32_e32 v14, v14, v18
	v_mul_f32_e32 v18, v10, v22
	v_mul_f32_e32 v10, v15, v19
	v_mul_f32_e32 v15, v11, v23
	v_mul_f32_e32 v11, v16, v20
	v_mul_f32_e32 v16, v12, v24
	v_mul_f32_e32 v12, v17, v21
	v_mul_f32_e32 v13, v13, v25
	v_cvt_pk_bf16_f32 v10, v14, v10
	v_cvt_pk_bf16_f32 v11, v11, v12
	v_cvt_pk_bf16_f32 v12, v18, v15
	v_cvt_pk_bf16_f32 v13, v16, v13
	global_load_dwordx4 v[14:17], v[38:39], off offset:256
	v_lshlrev_b64 v[18:19], 13, v[34:35]
	v_lshl_add_u64 v[18:19], s[12:13], 0, v[18:19]
	v_lshl_add_u64 v[18:19], v[18:19], 0, v[162:163]
	global_store_dwordx4 v[18:19], v[10:13], off
	s_waitcnt vmcnt(1)
	s_nop 0
	v_lshlrev_b32_e32 v10, 16, v14
	v_and_b32_e32 v11, 0xffff0000, v14
	v_lshlrev_b32_e32 v12, 16, v15
	v_and_b32_e32 v13, 0xffff0000, v15
	v_lshlrev_b32_e32 v14, 16, v16
	v_and_b32_e32 v15, 0xffff0000, v16
	v_lshlrev_b32_e32 v16, 16, v17
	v_and_b32_e32 v17, 0xffff0000, v17
	v_mul_f32_e32 v6, v6, v10
	v_mul_f32_e32 v10, v2, v14
	v_mul_f32_e32 v2, v7, v11
	v_mul_f32_e32 v7, v3, v15
	v_mul_f32_e32 v3, v8, v12
	v_mul_f32_e32 v8, v4, v16
	v_mul_f32_e32 v4, v9, v13
	v_mul_f32_e32 v5, v5, v17
	v_cvt_pk_bf16_f32 v2, v6, v2
	v_cvt_pk_bf16_f32 v3, v3, v4
	v_cvt_pk_bf16_f32 v4, v10, v7
	v_cvt_pk_bf16_f32 v5, v8, v5
	global_store_dwordx4 v[18:19], v[2:5], off offset:256
	s_cbranch_vccz .LBB0_507
	s_waitcnt vmcnt(0)
	s_cmpk_gt_u32 s24, 0xff
	s_cbranch_scc1 .LBB0_512
	s_barrier

.LBB0_595:
	s_add_i32 s62, s30, 2
	s_add_u32 s31, s28, 0xfff00080
	s_addc_u32 s34, s29, -1
	s_add_i32 s63, 0, 0x10000
	v_add_u32_e32 v148, s63, v1
	ds_read_b128 v[152:155], v148
	ds_read_b128 v[156:159], v148 offset:1024
	ds_read_b128 v[160:163], v148 offset:2048
	ds_read_b128 v[164:167], v148 offset:3072
	ds_read_b128 v[168:171], v150
	ds_read_b128 v[176:179], v150 offset:1024
	ds_read_b128 v[180:183], v150 offset:2048
	ds_read_b128 v[184:187], v150 offset:3072
	s_cmp_eq_u32 s25, s30
	s_cselect_b32 s30, s26, s60
	s_cselect_b32 s35, s15, s34
	s_cselect_b32 s34, s14, s31
	s_cselect_b32 s31, s27, s61
	v_lshl_add_u64 v[148:149], s[28:29], 0, v[142:143]
	s_add_i32 m0, s17, 0xc000
	ds_read_b128 v[188:191], v151
	ds_read_b128 v[192:195], v151 offset:1024
	ds_read_b128 v[196:199], v151 offset:2048
	ds_read_b128 v[200:203], v151 offset:3072
	ds_read_b128 v[204:207], v151 offset:4096
	ds_read_b128 v[208:211], v151 offset:5120
	ds_read_b128 v[212:215], v151 offset:6144
	ds_read_b128 v[216:219], v151 offset:7168
	global_load_lds_dwordx4 v[148:149], off
	v_lshl_add_u64 v[148:149], s[28:29], 0, v[144:145]
	s_add_i32 m0, s17, 0xe000
	s_nop 0
	global_load_lds_dwordx4 v[148:149], off
	s_waitcnt vmcnt(8)
	s_waitcnt lgkmcnt(0)
	s_setprio 1
	s_barrier
	v_mfma_f32_16x16x32_bf16 v[126:129], v[152:155], v[188:191], v[126:129]
	v_mfma_f32_16x16x32_bf16 v[122:125], v[160:163], v[188:191], v[122:125]
	v_mfma_f32_16x16x32_bf16 v[110:113], v[152:155], v[196:199], v[110:113]
	v_mfma_f32_16x16x32_bf16 v[106:109], v[160:163], v[196:199], v[106:109]
	v_mfma_f32_16x16x32_bf16 v[94:97], v[152:155], v[204:207], v[94:97]
	v_mfma_f32_16x16x32_bf16 v[90:93], v[160:163], v[204:207], v[90:93]
	v_mfma_f32_16x16x32_bf16 v[78:81], v[152:155], v[212:215], v[78:81]
	v_mfma_f32_16x16x32_bf16 v[74:77], v[160:163], v[212:215], v[74:77]
	v_mfma_f32_16x16x32_bf16 v[126:129], v[156:159], v[192:195], v[126:129]
	v_mfma_f32_16x16x32_bf16 v[122:125], v[164:167], v[192:195], v[122:125]
	v_mfma_f32_16x16x32_bf16 v[110:113], v[156:159], v[200:203], v[110:113]
	v_mfma_f32_16x16x32_bf16 v[106:109], v[164:167], v[200:203], v[106:109]
	v_mfma_f32_16x16x32_bf16 v[94:97], v[156:159], v[208:211], v[94:97]
	v_mfma_f32_16x16x32_bf16 v[90:93], v[164:167], v[208:211], v[90:93]
	v_mfma_f32_16x16x32_bf16 v[78:81], v[156:159], v[216:219], v[78:81]
	v_mfma_f32_16x16x32_bf16 v[74:77], v[164:167], v[216:219], v[74:77]
	v_mfma_f32_16x16x32_bf16 v[118:121], v[168:171], v[188:191], v[118:121]
	v_mfma_f32_16x16x32_bf16 v[114:117], v[180:183], v[188:191], v[114:117]
	v_mfma_f32_16x16x32_bf16 v[102:105], v[168:171], v[196:199], v[102:105]
	v_mfma_f32_16x16x32_bf16 v[98:101], v[180:183], v[196:199], v[98:101]
	v_mfma_f32_16x16x32_bf16 v[86:89], v[168:171], v[204:207], v[86:89]
	v_mfma_f32_16x16x32_bf16 v[82:85], v[180:183], v[204:207], v[82:85]
	v_mfma_f32_16x16x32_bf16 v[70:73], v[168:171], v[212:215], v[70:73]
	v_mfma_f32_16x16x32_bf16 v[66:69], v[180:183], v[212:215], v[66:69]
	v_mfma_f32_16x16x32_bf16 v[118:121], v[176:179], v[192:195], v[118:121]
	v_mfma_f32_16x16x32_bf16 v[114:117], v[184:187], v[192:195], v[114:117]
	v_mfma_f32_16x16x32_bf16 v[102:105], v[176:179], v[200:203], v[102:105]
	v_mfma_f32_16x16x32_bf16 v[98:101], v[184:187], v[200:203], v[98:101]
	v_mfma_f32_16x16x32_bf16 v[86:89], v[176:179], v[208:211], v[86:89]
	v_mfma_f32_16x16x32_bf16 v[82:85], v[184:187], v[208:211], v[82:85]
	v_mfma_f32_16x16x32_bf16 v[70:73], v[176:179], v[216:219], v[70:73]
	v_mfma_f32_16x16x32_bf16 v[66:69], v[184:187], v[216:219], v[66:69]
	s_barrier
	s_setprio 0
	s_add_i32 s63, s63, s43
	v_lshl_add_u64 v[148:149], s[30:31], 0, v[134:135]
	s_mov_b32 m0, s63
	ds_read_b128 v[188:191], v151 offset:16384
	ds_read_b128 v[192:195], v151 offset:17408
	ds_read_b128 v[196:199], v151 offset:18432
	ds_read_b128 v[200:203], v151 offset:19456
	ds_read_b128 v[204:207], v151 offset:20480
	ds_read_b128 v[208:211], v151 offset:21504
	ds_read_b128 v[212:215], v151 offset:22528
	ds_read_b128 v[216:219], v151 offset:23552
	global_load_lds_dwordx4 v[148:149], off
	s_add_i32 m0, s63, 0x2000
	s_add_u32 s64, s30, 0x100000
	v_lshl_add_u64 v[172:173], s[30:31], 0, v[130:131]
	s_addc_u32 s65, s31, 0
	s_add_i32 s63, s54, s43
	global_load_lds_dwordx4 v[172:173], off
	v_lshl_add_u64 v[220:221], s[64:65], 0, v[134:135]
	s_mov_b32 m0, s63
	v_lshl_add_u64 v[222:223], s[34:35], 0, v[132:133]
	global_load_lds_dwordx4 v[220:221], off
	v_lshl_add_u64 v[220:221], s[64:65], 0, v[130:131]
	s_add_i32 m0, s63, 0x2000
	s_nop 0
	global_load_lds_dwordx4 v[220:221], off
	v_lshl_add_u64 v[220:221], s[34:35], 0, v[136:137]
	s_mov_b32 m0, s17
	s_nop 0
	global_load_lds_dwordx4 v[220:221], off
	s_mov_b32 m0, s19
	s_nop 0
	global_load_lds_dwordx4 v[222:223], off
	s_waitcnt vmcnt(8)
	s_waitcnt lgkmcnt(0)
	s_setprio 1
	s_barrier
	v_mfma_f32_16x16x32_bf16 v[62:65], v[152:155], v[188:191], v[62:65]
	v_mfma_f32_16x16x32_bf16 v[58:61], v[160:163], v[188:191], v[58:61]
	v_mfma_f32_16x16x32_bf16 v[46:49], v[152:155], v[196:199], v[46:49]
	v_mfma_f32_16x16x32_bf16 v[42:45], v[160:163], v[196:199], v[42:45]
	v_mfma_f32_16x16x32_bf16 v[30:33], v[152:155], v[204:207], v[30:33]
	v_mfma_f32_16x16x32_bf16 v[26:29], v[160:163], v[204:207], v[26:29]
	v_mfma_f32_16x16x32_bf16 v[14:17], v[152:155], v[212:215], v[14:17]
	v_mfma_f32_16x16x32_bf16 v[10:13], v[160:163], v[212:215], v[10:13]
	v_mfma_f32_16x16x32_bf16 v[62:65], v[156:159], v[192:195], v[62:65]
	v_mfma_f32_16x16x32_bf16 v[58:61], v[164:167], v[192:195], v[58:61]
	v_mfma_f32_16x16x32_bf16 v[46:49], v[156:159], v[200:203], v[46:49]
	v_mfma_f32_16x16x32_bf16 v[42:45], v[164:167], v[200:203], v[42:45]
	v_mfma_f32_16x16x32_bf16 v[30:33], v[156:159], v[208:211], v[30:33]
	v_mfma_f32_16x16x32_bf16 v[26:29], v[164:167], v[208:211], v[26:29]
	v_mfma_f32_16x16x32_bf16 v[14:17], v[156:159], v[216:219], v[14:17]
	v_mfma_f32_16x16x32_bf16 v[10:13], v[164:167], v[216:219], v[10:13]
	v_mfma_f32_16x16x32_bf16 v[54:57], v[168:171], v[188:191], v[54:57]
	v_mfma_f32_16x16x32_bf16 v[50:53], v[180:183], v[188:191], v[50:53]
	v_mfma_f32_16x16x32_bf16 v[38:41], v[168:171], v[196:199], v[38:41]
	v_mfma_f32_16x16x32_bf16 v[34:37], v[180:183], v[196:199], v[34:37]
	v_mfma_f32_16x16x32_bf16 v[22:25], v[168:171], v[204:207], v[22:25]
	v_mfma_f32_16x16x32_bf16 v[18:21], v[180:183], v[204:207], v[18:21]
	v_mfma_f32_16x16x32_bf16 v[6:9], v[168:171], v[212:215], v[6:9]
	v_mfma_f32_16x16x32_bf16 v[2:5], v[180:183], v[212:215], v[2:5]
	v_mfma_f32_16x16x32_bf16 v[54:57], v[176:179], v[192:195], v[54:57]
	v_mfma_f32_16x16x32_bf16 v[50:53], v[184:187], v[192:195], v[50:53]
	v_mfma_f32_16x16x32_bf16 v[38:41], v[176:179], v[200:203], v[38:41]
	v_mfma_f32_16x16x32_bf16 v[34:37], v[184:187], v[200:203], v[34:37]
	v_mfma_f32_16x16x32_bf16 v[22:25], v[176:179], v[208:211], v[22:25]
	v_mfma_f32_16x16x32_bf16 v[18:21], v[184:187], v[208:211], v[18:21]
	v_mfma_f32_16x16x32_bf16 v[6:9], v[176:179], v[216:219], v[6:9]
	v_mfma_f32_16x16x32_bf16 v[2:5], v[184:187], v[216:219], v[2:5]
	s_barrier
	s_setprio 0
	s_add_i32 s63, 0, 0x18000
	s_add_i32 s64, 0, 0x1c000
	v_add_u32_e32 v164, s63, v1
	v_add_u32_e32 v175, s64, v1
	ds_read_b128 v[152:155], v164
	ds_read_b128 v[156:159], v164 offset:1024
	ds_read_b128 v[160:163], v164 offset:2048
	ds_read_b128 v[164:167], v164 offset:3072
	ds_read_b128 v[168:171], v175
	ds_read_b128 v[176:179], v175 offset:1024
	ds_read_b128 v[180:183], v175 offset:2048
	ds_read_b128 v[184:187], v175 offset:3072
	s_add_u32 s34, s34, 0x100000
	s_addc_u32 s35, s35, 0
	s_mov_b32 m0, s44
	v_lshl_add_u64 v[224:225], s[34:35], 0, v[136:137]
	ds_read_b128 v[188:191], v151 offset:32768
	ds_read_b128 v[192:195], v151 offset:33792
	ds_read_b128 v[196:199], v151 offset:34816
	ds_read_b128 v[200:203], v151 offset:35840
	ds_read_b128 v[204:207], v151 offset:36864
	ds_read_b128 v[208:211], v151 offset:37888
	ds_read_b128 v[212:215], v151 offset:38912
	ds_read_b128 v[216:219], v151 offset:39936
	global_load_lds_dwordx4 v[224:225], off
	v_lshl_add_u64 v[224:225], s[34:35], 0, v[132:133]
	s_mov_b32 m0, s45
	s_nop 0
	global_load_lds_dwordx4 v[224:225], off
	s_waitcnt vmcnt(8)
	s_waitcnt lgkmcnt(0)
	s_setprio 1
	s_barrier
	v_mfma_f32_16x16x32_bf16 v[126:129], v[152:155], v[188:191], v[126:129]
	v_mfma_f32_16x16x32_bf16 v[122:125], v[160:163], v[188:191], v[122:125]
	v_mfma_f32_16x16x32_bf16 v[110:113], v[152:155], v[196:199], v[110:113]
	v_mfma_f32_16x16x32_bf16 v[106:109], v[160:163], v[196:199], v[106:109]
	v_mfma_f32_16x16x32_bf16 v[94:97], v[152:155], v[204:207], v[94:97]
	v_mfma_f32_16x16x32_bf16 v[90:93], v[160:163], v[204:207], v[90:93]
	v_mfma_f32_16x16x32_bf16 v[78:81], v[152:155], v[212:215], v[78:81]
	v_mfma_f32_16x16x32_bf16 v[74:77], v[160:163], v[212:215], v[74:77]
	v_mfma_f32_16x16x32_bf16 v[126:129], v[156:159], v[192:195], v[126:129]
	v_mfma_f32_16x16x32_bf16 v[122:125], v[164:167], v[192:195], v[122:125]
	v_mfma_f32_16x16x32_bf16 v[110:113], v[156:159], v[200:203], v[110:113]
	v_mfma_f32_16x16x32_bf16 v[106:109], v[164:167], v[200:203], v[106:109]
	v_mfma_f32_16x16x32_bf16 v[94:97], v[156:159], v[208:211], v[94:97]
	v_mfma_f32_16x16x32_bf16 v[90:93], v[164:167], v[208:211], v[90:93]
	v_mfma_f32_16x16x32_bf16 v[78:81], v[156:159], v[216:219], v[78:81]
	v_mfma_f32_16x16x32_bf16 v[74:77], v[164:167], v[216:219], v[74:77]
	v_mfma_f32_16x16x32_bf16 v[118:121], v[168:171], v[188:191], v[118:121]
	v_mfma_f32_16x16x32_bf16 v[114:117], v[180:183], v[188:191], v[114:117]
	v_mfma_f32_16x16x32_bf16 v[102:105], v[168:171], v[196:199], v[102:105]
	v_mfma_f32_16x16x32_bf16 v[98:101], v[180:183], v[196:199], v[98:101]
	v_mfma_f32_16x16x32_bf16 v[86:89], v[168:171], v[204:207], v[86:89]
	v_mfma_f32_16x16x32_bf16 v[82:85], v[180:183], v[204:207], v[82:85]
	v_mfma_f32_16x16x32_bf16 v[70:73], v[168:171], v[212:215], v[70:73]
	v_mfma_f32_16x16x32_bf16 v[66:69], v[180:183], v[212:215], v[66:69]
	v_mfma_f32_16x16x32_bf16 v[118:121], v[176:179], v[192:195], v[118:121]
	v_mfma_f32_16x16x32_bf16 v[114:117], v[184:187], v[192:195], v[114:117]
	v_mfma_f32_16x16x32_bf16 v[102:105], v[176:179], v[200:203], v[102:105]
	v_mfma_f32_16x16x32_bf16 v[98:101], v[184:187], v[200:203], v[98:101]
	v_mfma_f32_16x16x32_bf16 v[86:89], v[176:179], v[208:211], v[86:89]
	v_mfma_f32_16x16x32_bf16 v[82:85], v[184:187], v[208:211], v[82:85]
	v_mfma_f32_16x16x32_bf16 v[70:73], v[176:179], v[216:219], v[70:73]
	v_mfma_f32_16x16x32_bf16 v[66:69], v[184:187], v[216:219], v[66:69]
	s_barrier
	s_setprio 0
	s_add_i32 s34, s63, s43
	v_lshl_add_u64 v[148:149], v[148:149], 0, s[6:7]
	s_mov_b32 m0, s34
	ds_read_b128 v[188:191], v151 offset:49152
	ds_read_b128 v[192:195], v151 offset:50176
	ds_read_b128 v[196:199], v151 offset:51200
	ds_read_b128 v[200:203], v151 offset:52224
	ds_read_b128 v[204:207], v151 offset:53248
	ds_read_b128 v[208:211], v151 offset:54272
	ds_read_b128 v[212:215], v151 offset:55296
	ds_read_b128 v[216:219], v151 offset:56320
	global_load_lds_dwordx4 v[148:149], off
	s_add_i32 m0, s34, 0x2000
	s_add_u32 s30, s30, 0x100080
	v_lshl_add_u64 v[148:149], v[172:173], 0, s[6:7]
	s_addc_u32 s31, s31, 0
	s_add_i32 s34, s64, s43
	global_load_lds_dwordx4 v[148:149], off
	v_lshl_add_u64 v[148:149], s[30:31], 0, v[134:135]
	s_mov_b32 m0, s34
	s_nop 0
	global_load_lds_dwordx4 v[148:149], off
	v_lshl_add_u64 v[148:149], s[30:31], 0, v[130:131]
	s_add_i32 m0, s34, 0x2000
	s_nop 0
	global_load_lds_dwordx4 v[148:149], off
	v_lshl_add_u64 v[148:149], v[220:221], 0, s[6:7]
	s_mov_b32 m0, s51
	s_nop 0
	global_load_lds_dwordx4 v[148:149], off
	v_lshl_add_u64 v[148:149], v[222:223], 0, s[6:7]
	s_mov_b32 m0, s52
	s_nop 0
	global_load_lds_dwordx4 v[148:149], off
	s_waitcnt vmcnt(8)
	s_waitcnt lgkmcnt(0)
	s_setprio 1
	s_barrier
	v_mfma_f32_16x16x32_bf16 v[62:65], v[152:155], v[188:191], v[62:65]
	v_mfma_f32_16x16x32_bf16 v[58:61], v[160:163], v[188:191], v[58:61]
	v_mfma_f32_16x16x32_bf16 v[46:49], v[152:155], v[196:199], v[46:49]
	v_mfma_f32_16x16x32_bf16 v[42:45], v[160:163], v[196:199], v[42:45]
	v_mfma_f32_16x16x32_bf16 v[30:33], v[152:155], v[204:207], v[30:33]
	v_mfma_f32_16x16x32_bf16 v[26:29], v[160:163], v[204:207], v[26:29]
	v_mfma_f32_16x16x32_bf16 v[14:17], v[152:155], v[212:215], v[14:17]
	v_mfma_f32_16x16x32_bf16 v[10:13], v[160:163], v[212:215], v[10:13]
	v_mfma_f32_16x16x32_bf16 v[62:65], v[156:159], v[192:195], v[62:65]
	v_mfma_f32_16x16x32_bf16 v[58:61], v[164:167], v[192:195], v[58:61]
	v_mfma_f32_16x16x32_bf16 v[46:49], v[156:159], v[200:203], v[46:49]
	v_mfma_f32_16x16x32_bf16 v[42:45], v[164:167], v[200:203], v[42:45]
	v_mfma_f32_16x16x32_bf16 v[30:33], v[156:159], v[208:211], v[30:33]
	v_mfma_f32_16x16x32_bf16 v[26:29], v[164:167], v[208:211], v[26:29]
	v_mfma_f32_16x16x32_bf16 v[14:17], v[156:159], v[216:219], v[14:17]
	v_mfma_f32_16x16x32_bf16 v[10:13], v[164:167], v[216:219], v[10:13]
	v_mfma_f32_16x16x32_bf16 v[54:57], v[168:171], v[188:191], v[54:57]
	v_mfma_f32_16x16x32_bf16 v[50:53], v[180:183], v[188:191], v[50:53]
	v_mfma_f32_16x16x32_bf16 v[38:41], v[168:171], v[196:199], v[38:41]
	v_mfma_f32_16x16x32_bf16 v[34:37], v[180:183], v[196:199], v[34:37]
	v_mfma_f32_16x16x32_bf16 v[22:25], v[168:171], v[204:207], v[22:25]
	v_mfma_f32_16x16x32_bf16 v[18:21], v[180:183], v[204:207], v[18:21]
	v_mfma_f32_16x16x32_bf16 v[6:9], v[168:171], v[212:215], v[6:9]
	v_mfma_f32_16x16x32_bf16 v[2:5], v[180:183], v[212:215], v[2:5]
	v_mfma_f32_16x16x32_bf16 v[54:57], v[176:179], v[192:195], v[54:57]
	v_mfma_f32_16x16x32_bf16 v[50:53], v[184:187], v[192:195], v[50:53]
	v_mfma_f32_16x16x32_bf16 v[38:41], v[176:179], v[200:203], v[38:41]
	v_mfma_f32_16x16x32_bf16 v[34:37], v[184:187], v[200:203], v[34:37]
	v_mfma_f32_16x16x32_bf16 v[22:25], v[176:179], v[208:211], v[22:25]
	v_mfma_f32_16x16x32_bf16 v[18:21], v[184:187], v[208:211], v[18:21]
	v_mfma_f32_16x16x32_bf16 v[6:9], v[176:179], v[216:219], v[6:9]
	v_mfma_f32_16x16x32_bf16 v[2:5], v[184:187], v[216:219], v[2:5]
	s_barrier
	s_setprio 0
	s_add_u32 s28, s28, 0x100
	s_addc_u32 s29, s29, 0
	s_add_u32 s60, s60, 0x100
	s_addc_u32 s61, s61, 0
	s_cmp_ge_u32 s62, s21
	s_mov_b32 s30, s62
	s_cbranch_scc0 .LBB0_595
	s_ashr_i32 s2, s2, 20
	s_cmp_gt_i32 s2, 0
	s_mov_b64 s[28:29], -1
	s_cbranch_scc0 .LBB0_598

.LBB0_731:
	ds_read_b128 v[148:151], v156
	ds_read_b128 v[160:163], v156 offset:1024
	ds_read_b128 v[164:167], v156 offset:2048
	ds_read_b128 v[168:171], v156 offset:3072
	ds_read_b128 v[176:179], v157
	ds_read_b128 v[180:183], v157 offset:1024
	ds_read_b128 v[184:187], v157 offset:2048
	ds_read_b128 v[188:191], v157 offset:3072
	s_add_u32 s22, s0, 0xfff00080
	s_addc_u32 s23, s1, -1
	s_cmp_eq_u32 s61, 60
	s_cselect_b32 s25, s5, s23
	s_cselect_b32 s24, s57, s22
	s_cselect_b32 s23, s21, s60
	s_cselect_b32 s22, s58, s59
	v_lshl_add_u64 v[152:153], s[0:1], 0, v[140:141]
	s_add_i32 m0, s34, 0xc000
	ds_read_b128 v[192:195], v158
	ds_read_b128 v[196:199], v158 offset:1024
	ds_read_b128 v[200:203], v158 offset:2048
	ds_read_b128 v[204:207], v158 offset:3072
	ds_read_b128 v[208:211], v158 offset:4096
	ds_read_b128 v[212:215], v158 offset:5120
	ds_read_b128 v[216:219], v158 offset:6144
	ds_read_b128 v[220:223], v158 offset:7168
	global_load_lds_dwordx4 v[152:153], off
	v_lshl_add_u64 v[152:153], s[0:1], 0, v[142:143]
	s_add_i32 m0, s34, 0xe000
	s_nop 0
	global_load_lds_dwordx4 v[152:153], off
	s_waitcnt vmcnt(8)
	s_waitcnt lgkmcnt(0)
	s_setprio 1
	s_barrier
	v_mfma_f32_16x16x32_bf16 v[126:129], v[148:151], v[192:195], v[126:129]
	v_mfma_f32_16x16x32_bf16 v[122:125], v[164:167], v[192:195], v[122:125]
	v_mfma_f32_16x16x32_bf16 v[110:113], v[148:151], v[200:203], v[110:113]
	v_mfma_f32_16x16x32_bf16 v[106:109], v[164:167], v[200:203], v[106:109]
	v_mfma_f32_16x16x32_bf16 v[94:97], v[148:151], v[208:211], v[94:97]
	v_mfma_f32_16x16x32_bf16 v[90:93], v[164:167], v[208:211], v[90:93]
	v_mfma_f32_16x16x32_bf16 v[78:81], v[148:151], v[216:219], v[78:81]
	v_mfma_f32_16x16x32_bf16 v[74:77], v[164:167], v[216:219], v[74:77]
	v_mfma_f32_16x16x32_bf16 v[126:129], v[160:163], v[196:199], v[126:129]
	v_mfma_f32_16x16x32_bf16 v[122:125], v[168:171], v[196:199], v[122:125]
	v_mfma_f32_16x16x32_bf16 v[110:113], v[160:163], v[204:207], v[110:113]
	v_mfma_f32_16x16x32_bf16 v[106:109], v[168:171], v[204:207], v[106:109]
	v_mfma_f32_16x16x32_bf16 v[94:97], v[160:163], v[212:215], v[94:97]
	v_mfma_f32_16x16x32_bf16 v[90:93], v[168:171], v[212:215], v[90:93]
	v_mfma_f32_16x16x32_bf16 v[78:81], v[160:163], v[220:223], v[78:81]
	v_mfma_f32_16x16x32_bf16 v[74:77], v[168:171], v[220:223], v[74:77]
	v_mfma_f32_16x16x32_bf16 v[118:121], v[176:179], v[192:195], v[118:121]
	v_mfma_f32_16x16x32_bf16 v[114:117], v[184:187], v[192:195], v[114:117]
	v_mfma_f32_16x16x32_bf16 v[102:105], v[176:179], v[200:203], v[102:105]
	v_mfma_f32_16x16x32_bf16 v[98:101], v[184:187], v[200:203], v[98:101]
	v_mfma_f32_16x16x32_bf16 v[86:89], v[176:179], v[208:211], v[86:89]
	v_mfma_f32_16x16x32_bf16 v[82:85], v[184:187], v[208:211], v[82:85]
	v_mfma_f32_16x16x32_bf16 v[70:73], v[176:179], v[216:219], v[70:73]
	v_mfma_f32_16x16x32_bf16 v[66:69], v[184:187], v[216:219], v[66:69]
	v_mfma_f32_16x16x32_bf16 v[118:121], v[180:183], v[196:199], v[118:121]
	v_mfma_f32_16x16x32_bf16 v[114:117], v[188:191], v[196:199], v[114:117]
	v_mfma_f32_16x16x32_bf16 v[102:105], v[180:183], v[204:207], v[102:105]
	v_mfma_f32_16x16x32_bf16 v[98:101], v[188:191], v[204:207], v[98:101]
	v_mfma_f32_16x16x32_bf16 v[86:89], v[180:183], v[212:215], v[86:89]
	v_mfma_f32_16x16x32_bf16 v[82:85], v[188:191], v[212:215], v[82:85]
	v_mfma_f32_16x16x32_bf16 v[70:73], v[180:183], v[220:223], v[70:73]
	v_mfma_f32_16x16x32_bf16 v[66:69], v[188:191], v[220:223], v[66:69]
	s_barrier
	s_setprio 0
	s_add_i32 s62, s44, s31
	v_lshl_add_u64 v[152:153], s[22:23], 0, v[136:137]
	s_mov_b32 m0, s62
	ds_read_b128 v[192:195], v158 offset:16384
	ds_read_b128 v[196:199], v158 offset:17408
	ds_read_b128 v[200:203], v158 offset:18432
	ds_read_b128 v[204:207], v158 offset:19456
	ds_read_b128 v[208:211], v158 offset:20480
	ds_read_b128 v[212:215], v158 offset:21504
	ds_read_b128 v[216:219], v158 offset:22528
	ds_read_b128 v[220:223], v158 offset:23552
	global_load_lds_dwordx4 v[152:153], off
	s_add_i32 m0, s62, 0x2000
	s_add_u32 s62, s22, 0x100000
	v_lshl_add_u64 v[172:173], s[22:23], 0, v[130:131]
	s_addc_u32 s63, s23, 0
	s_add_i32 s64, s45, s31
	global_load_lds_dwordx4 v[172:173], off
	v_lshl_add_u64 v[224:225], s[62:63], 0, v[136:137]
	s_mov_b32 m0, s64
	v_lshl_add_u64 v[226:227], s[24:25], 0, v[132:133]
	global_load_lds_dwordx4 v[224:225], off
	v_lshl_add_u64 v[224:225], s[62:63], 0, v[130:131]
	s_add_i32 m0, s64, 0x2000
	s_nop 0
	global_load_lds_dwordx4 v[224:225], off
	v_lshl_add_u64 v[224:225], s[24:25], 0, v[138:139]
	s_mov_b32 m0, s34
	s_nop 0
	global_load_lds_dwordx4 v[224:225], off
	s_mov_b32 m0, s35
	s_nop 0
	global_load_lds_dwordx4 v[226:227], off
	s_waitcnt vmcnt(8)
	s_waitcnt lgkmcnt(0)
	s_setprio 1
	s_barrier
	v_mfma_f32_16x16x32_bf16 v[62:65], v[148:151], v[192:195], v[62:65]
	v_mfma_f32_16x16x32_bf16 v[58:61], v[164:167], v[192:195], v[58:61]
	v_mfma_f32_16x16x32_bf16 v[46:49], v[148:151], v[200:203], v[46:49]
	v_mfma_f32_16x16x32_bf16 v[42:45], v[164:167], v[200:203], v[42:45]
	v_mfma_f32_16x16x32_bf16 v[30:33], v[148:151], v[208:211], v[30:33]
	v_mfma_f32_16x16x32_bf16 v[26:29], v[164:167], v[208:211], v[26:29]
	v_mfma_f32_16x16x32_bf16 v[14:17], v[148:151], v[216:219], v[14:17]
	v_mfma_f32_16x16x32_bf16 v[10:13], v[164:167], v[216:219], v[10:13]
	v_mfma_f32_16x16x32_bf16 v[62:65], v[160:163], v[196:199], v[62:65]
	v_mfma_f32_16x16x32_bf16 v[58:61], v[168:171], v[196:199], v[58:61]
	v_mfma_f32_16x16x32_bf16 v[46:49], v[160:163], v[204:207], v[46:49]
	v_mfma_f32_16x16x32_bf16 v[42:45], v[168:171], v[204:207], v[42:45]
	v_mfma_f32_16x16x32_bf16 v[30:33], v[160:163], v[212:215], v[30:33]
	v_mfma_f32_16x16x32_bf16 v[26:29], v[168:171], v[212:215], v[26:29]
	v_mfma_f32_16x16x32_bf16 v[14:17], v[160:163], v[220:223], v[14:17]
	v_mfma_f32_16x16x32_bf16 v[10:13], v[168:171], v[220:223], v[10:13]
	v_mfma_f32_16x16x32_bf16 v[54:57], v[176:179], v[192:195], v[54:57]
	v_mfma_f32_16x16x32_bf16 v[50:53], v[184:187], v[192:195], v[50:53]
	v_mfma_f32_16x16x32_bf16 v[38:41], v[176:179], v[200:203], v[38:41]
	v_mfma_f32_16x16x32_bf16 v[34:37], v[184:187], v[200:203], v[34:37]
	v_mfma_f32_16x16x32_bf16 v[22:25], v[176:179], v[208:211], v[22:25]
	v_mfma_f32_16x16x32_bf16 v[18:21], v[184:187], v[208:211], v[18:21]
	v_mfma_f32_16x16x32_bf16 v[6:9], v[176:179], v[216:219], v[6:9]
	v_mfma_f32_16x16x32_bf16 v[2:5], v[184:187], v[216:219], v[2:5]
	v_mfma_f32_16x16x32_bf16 v[54:57], v[180:183], v[196:199], v[54:57]
	v_mfma_f32_16x16x32_bf16 v[50:53], v[188:191], v[196:199], v[50:53]
	v_mfma_f32_16x16x32_bf16 v[38:41], v[180:183], v[204:207], v[38:41]
	v_mfma_f32_16x16x32_bf16 v[34:37], v[188:191], v[204:207], v[34:37]
	v_mfma_f32_16x16x32_bf16 v[22:25], v[180:183], v[212:215], v[22:25]
	v_mfma_f32_16x16x32_bf16 v[18:21], v[188:191], v[212:215], v[18:21]
	v_mfma_f32_16x16x32_bf16 v[6:9], v[180:183], v[220:223], v[6:9]
	v_mfma_f32_16x16x32_bf16 v[2:5], v[188:191], v[220:223], v[2:5]
	s_barrier
	s_setprio 0
	s_add_i32 s62, 0, 0x18000
	v_add_u32_e32 v159, s62, v135
	s_add_i32 s63, 0, 0x1c000
	ds_read_b128 v[148:151], v159
	ds_read_b128 v[160:163], v159 offset:1024
	ds_read_b128 v[164:167], v159 offset:2048
	ds_read_b128 v[168:171], v159 offset:3072
	v_add_u32_e32 v159, s63, v135
	ds_read_b128 v[176:179], v159
	ds_read_b128 v[180:183], v159 offset:1024
	ds_read_b128 v[184:187], v159 offset:2048
	ds_read_b128 v[188:191], v159 offset:3072
	s_add_u32 s24, s24, 0x100000
	s_addc_u32 s25, s25, 0
	s_mov_b32 m0, s36
	v_lshl_add_u64 v[228:229], s[24:25], 0, v[138:139]
	ds_read_b128 v[192:195], v158 offset:32768
	ds_read_b128 v[196:199], v158 offset:33792
	ds_read_b128 v[200:203], v158 offset:34816
	ds_read_b128 v[204:207], v158 offset:35840
	ds_read_b128 v[208:211], v158 offset:36864
	ds_read_b128 v[212:215], v158 offset:37888
	ds_read_b128 v[216:219], v158 offset:38912
	ds_read_b128 v[220:223], v158 offset:39936
	global_load_lds_dwordx4 v[228:229], off
	v_lshl_add_u64 v[228:229], s[24:25], 0, v[132:133]
	s_mov_b32 m0, s37
	s_nop 0
	global_load_lds_dwordx4 v[228:229], off
	s_waitcnt vmcnt(8)
	s_waitcnt lgkmcnt(0)
	s_setprio 1
	s_barrier
	v_mfma_f32_16x16x32_bf16 v[126:129], v[148:151], v[192:195], v[126:129]
	v_mfma_f32_16x16x32_bf16 v[122:125], v[164:167], v[192:195], v[122:125]
	v_mfma_f32_16x16x32_bf16 v[110:113], v[148:151], v[200:203], v[110:113]
	v_mfma_f32_16x16x32_bf16 v[106:109], v[164:167], v[200:203], v[106:109]
	v_mfma_f32_16x16x32_bf16 v[94:97], v[148:151], v[208:211], v[94:97]
	v_mfma_f32_16x16x32_bf16 v[90:93], v[164:167], v[208:211], v[90:93]
	v_mfma_f32_16x16x32_bf16 v[78:81], v[148:151], v[216:219], v[78:81]
	v_mfma_f32_16x16x32_bf16 v[74:77], v[164:167], v[216:219], v[74:77]
	v_mfma_f32_16x16x32_bf16 v[126:129], v[160:163], v[196:199], v[126:129]
	v_mfma_f32_16x16x32_bf16 v[122:125], v[168:171], v[196:199], v[122:125]
	v_mfma_f32_16x16x32_bf16 v[110:113], v[160:163], v[204:207], v[110:113]
	v_mfma_f32_16x16x32_bf16 v[106:109], v[168:171], v[204:207], v[106:109]
	v_mfma_f32_16x16x32_bf16 v[94:97], v[160:163], v[212:215], v[94:97]
	v_mfma_f32_16x16x32_bf16 v[90:93], v[168:171], v[212:215], v[90:93]
	v_mfma_f32_16x16x32_bf16 v[78:81], v[160:163], v[220:223], v[78:81]
	v_mfma_f32_16x16x32_bf16 v[74:77], v[168:171], v[220:223], v[74:77]
	v_mfma_f32_16x16x32_bf16 v[118:121], v[176:179], v[192:195], v[118:121]
	v_mfma_f32_16x16x32_bf16 v[114:117], v[184:187], v[192:195], v[114:117]
	v_mfma_f32_16x16x32_bf16 v[102:105], v[176:179], v[200:203], v[102:105]
	v_mfma_f32_16x16x32_bf16 v[98:101], v[184:187], v[200:203], v[98:101]
	v_mfma_f32_16x16x32_bf16 v[86:89], v[176:179], v[208:211], v[86:89]
	v_mfma_f32_16x16x32_bf16 v[82:85], v[184:187], v[208:211], v[82:85]
	v_mfma_f32_16x16x32_bf16 v[70:73], v[176:179], v[216:219], v[70:73]
	v_mfma_f32_16x16x32_bf16 v[66:69], v[184:187], v[216:219], v[66:69]
	v_mfma_f32_16x16x32_bf16 v[118:121], v[180:183], v[196:199], v[118:121]
	v_mfma_f32_16x16x32_bf16 v[114:117], v[188:191], v[196:199], v[114:117]
	v_mfma_f32_16x16x32_bf16 v[102:105], v[180:183], v[204:207], v[102:105]
	v_mfma_f32_16x16x32_bf16 v[98:101], v[188:191], v[204:207], v[98:101]
	v_mfma_f32_16x16x32_bf16 v[86:89], v[180:183], v[212:215], v[86:89]
	v_mfma_f32_16x16x32_bf16 v[82:85], v[188:191], v[212:215], v[82:85]
	v_mfma_f32_16x16x32_bf16 v[70:73], v[180:183], v[220:223], v[70:73]
	v_mfma_f32_16x16x32_bf16 v[66:69], v[188:191], v[220:223], v[66:69]
	s_barrier
	s_setprio 0
	s_add_i32 s24, s62, s31
	v_lshl_add_u64 v[152:153], v[152:153], 0, s[16:17]
	s_mov_b32 m0, s24
	ds_read_b128 v[192:195], v158 offset:49152
	ds_read_b128 v[196:199], v158 offset:50176
	ds_read_b128 v[200:203], v158 offset:51200
	ds_read_b128 v[204:207], v158 offset:52224
	ds_read_b128 v[208:211], v158 offset:53248
	ds_read_b128 v[212:215], v158 offset:54272
	ds_read_b128 v[216:219], v158 offset:55296
	ds_read_b128 v[220:223], v158 offset:56320
	global_load_lds_dwordx4 v[152:153], off
	s_add_i32 m0, s24, 0x2000
	s_add_u32 s22, s22, 0x100080
	v_lshl_add_u64 v[152:153], v[172:173], 0, s[16:17]
	s_addc_u32 s23, s23, 0
	s_add_i32 s24, s63, s31
	global_load_lds_dwordx4 v[152:153], off
	v_lshl_add_u64 v[152:153], s[22:23], 0, v[136:137]
	s_mov_b32 m0, s24
	s_nop 0
	global_load_lds_dwordx4 v[152:153], off
	v_lshl_add_u64 v[152:153], s[22:23], 0, v[130:131]
	s_add_i32 m0, s24, 0x2000
	s_nop 0
	global_load_lds_dwordx4 v[152:153], off
	v_lshl_add_u64 v[152:153], v[224:225], 0, s[16:17]
	s_mov_b32 m0, s40
	s_nop 0
	global_load_lds_dwordx4 v[152:153], off
	v_lshl_add_u64 v[152:153], v[226:227], 0, s[16:17]
	s_mov_b32 m0, s41
	s_nop 0
	global_load_lds_dwordx4 v[152:153], off
	s_waitcnt vmcnt(8)
	s_waitcnt lgkmcnt(0)
	s_setprio 1
	s_barrier
	v_mfma_f32_16x16x32_bf16 v[62:65], v[148:151], v[192:195], v[62:65]
	v_mfma_f32_16x16x32_bf16 v[58:61], v[164:167], v[192:195], v[58:61]
	v_mfma_f32_16x16x32_bf16 v[46:49], v[148:151], v[200:203], v[46:49]
	v_mfma_f32_16x16x32_bf16 v[42:45], v[164:167], v[200:203], v[42:45]
	v_mfma_f32_16x16x32_bf16 v[30:33], v[148:151], v[208:211], v[30:33]
	v_mfma_f32_16x16x32_bf16 v[26:29], v[164:167], v[208:211], v[26:29]
	v_mfma_f32_16x16x32_bf16 v[14:17], v[148:151], v[216:219], v[14:17]
	v_mfma_f32_16x16x32_bf16 v[10:13], v[164:167], v[216:219], v[10:13]
	v_mfma_f32_16x16x32_bf16 v[62:65], v[160:163], v[196:199], v[62:65]
	v_mfma_f32_16x16x32_bf16 v[58:61], v[168:171], v[196:199], v[58:61]
	v_mfma_f32_16x16x32_bf16 v[46:49], v[160:163], v[204:207], v[46:49]
	v_mfma_f32_16x16x32_bf16 v[42:45], v[168:171], v[204:207], v[42:45]
	v_mfma_f32_16x16x32_bf16 v[30:33], v[160:163], v[212:215], v[30:33]
	v_mfma_f32_16x16x32_bf16 v[26:29], v[168:171], v[212:215], v[26:29]
	v_mfma_f32_16x16x32_bf16 v[14:17], v[160:163], v[220:223], v[14:17]
	v_mfma_f32_16x16x32_bf16 v[10:13], v[168:171], v[220:223], v[10:13]
	v_mfma_f32_16x16x32_bf16 v[54:57], v[176:179], v[192:195], v[54:57]
	v_mfma_f32_16x16x32_bf16 v[50:53], v[184:187], v[192:195], v[50:53]
	v_mfma_f32_16x16x32_bf16 v[38:41], v[176:179], v[200:203], v[38:41]
	v_mfma_f32_16x16x32_bf16 v[34:37], v[184:187], v[200:203], v[34:37]
	v_mfma_f32_16x16x32_bf16 v[22:25], v[176:179], v[208:211], v[22:25]
	v_mfma_f32_16x16x32_bf16 v[18:21], v[184:187], v[208:211], v[18:21]
	v_mfma_f32_16x16x32_bf16 v[6:9], v[176:179], v[216:219], v[6:9]
	v_mfma_f32_16x16x32_bf16 v[2:5], v[184:187], v[216:219], v[2:5]
	v_mfma_f32_16x16x32_bf16 v[54:57], v[180:183], v[196:199], v[54:57]
	v_mfma_f32_16x16x32_bf16 v[50:53], v[188:191], v[196:199], v[50:53]
	v_mfma_f32_16x16x32_bf16 v[38:41], v[180:183], v[204:207], v[38:41]
	v_mfma_f32_16x16x32_bf16 v[34:37], v[188:191], v[204:207], v[34:37]
	v_mfma_f32_16x16x32_bf16 v[22:25], v[180:183], v[212:215], v[22:25]
	v_mfma_f32_16x16x32_bf16 v[18:21], v[188:191], v[212:215], v[18:21]
	v_mfma_f32_16x16x32_bf16 v[6:9], v[180:183], v[220:223], v[6:9]
	v_mfma_f32_16x16x32_bf16 v[2:5], v[188:191], v[220:223], v[2:5]
	s_barrier
	s_setprio 0
	s_add_i32 s61, s61, 2
	s_add_u32 s0, s0, 0x100
	s_addc_u32 s1, s1, 0
	s_add_u32 s59, s59, 0x100
	s_addc_u32 s60, s60, 0
	s_cmp_gt_u32 s61, 61
	s_cbranch_scc0 .LBB0_731
	v_and_b32_e32 v165, 3, v174
	v_lshrrev_b32_e32 v170, 2, v174
	v_lshlrev_b32_e32 v164, 6, v165
	v_and_or_b32 v164, v174, 60, v164
	v_and_b32_e32 v171, 15, v174
	v_sub_u32_e32 v170, v170, v171
	v_lshrrev_b32_e32 v171, 4, v174
	v_sub_u32_e32 v165, v165, v171
	v_mul_i32_i24_e32 v170, 0xac00, v170
	v_lshl_add_u32 v166, v165, 4, v170
	v_ashrrev_i32_e32 v167, 31, v166
	s_lshl_b32 s5, s56, 8
	s_add_i32 s5, s5, s39
	v_or_b32_e32 v159, s5, v1
	v_cmp_lt_i32_e64 s[0:1], s46, v159
	s_and_b64 s[22:23], s[0:1], s[18:19]
	v_mov_b64_e32 v[150:151], 0
	s_and_saveexec_b64 s[0:1], s[22:23]
	v_add_u32_e32 v148, 0xffffe000, v159
	v_lshrrev_b32_e32 v148, 2, v148
	v_and_b32_e32 v148, 0x3ffffff2, v148
	v_add_u32_e32 v150, v148, v154
	v_mov_b64_e32 v[148:149], s[10:11]
	v_mad_u64_u32 v[150:151], s[22:23], v150, s47, v[148:149]
	s_or_b64 exec, exec, s[0:1]
	v_lshl_or_b32 v148, s55, 8, v155
	v_mov_b64_e32 v[152:153], s[6:7]
	v_ashrrev_i32_e32 v149, 31, v148
	v_mad_i64_i32 v[152:153], s[0:1], v159, s48, v[152:153]
	v_lshl_add_u64 v[152:153], v[148:149], 1, v[152:153]
	v_cmp_ne_u64_e64 s[0:1], 0, v[150:151]
	v_lshl_add_u64 v[150:151], v[148:149], 2, v[150:151]
	v_cvt_pk_bf16_f32 v160, v126, v127
	v_cvt_pk_bf16_f32 v161, v128, v129
	v_cvt_pk_bf16_f32 v162, v122, v123
	v_cvt_pk_bf16_f32 v163, v124, v125
	ds_bpermute_b32 v160, v164, v160
	ds_bpermute_b32 v161, v164, v161
	ds_bpermute_b32 v162, v164, v162
	ds_bpermute_b32 v163, v164, v163
	v_lshl_add_u64 v[168:169], v[166:167], 0, v[152:153]
	s_waitcnt lgkmcnt(0)
	global_store_dwordx4 v[168:169], v[160:163], off
	s_and_saveexec_b64 s[22:23], s[0:1]
	s_cbranch_execz .LBB0_736
	global_store_dwordx4 v[150:151], v[126:129], off
	global_store_dwordx4 v[150:151], v[122:125], off offset:16

.LBB0_931:
	ds_read_b128 v[154:157], v141
	ds_read_b128 v[158:161], v141 offset:1024
	ds_read_b128 v[162:165], v141 offset:2048
	ds_read_b128 v[166:169], v141 offset:3072
	ds_read_b128 v[170:173], v152
	ds_read_b128 v[176:179], v152 offset:1024
	ds_read_b128 v[180:183], v152 offset:2048
	ds_read_b128 v[184:187], v152 offset:3072
	s_add_i32 s73, s24, 2
	s_add_u32 s25, s22, 0xffd50080
	s_addc_u32 s26, s23, -1
	s_cmp_eq_u32 s70, s24
	s_cselect_b32 s24, s20, s71
	s_cselect_b32 s27, s17, s26
	s_cselect_b32 s26, s16, s25
	s_cselect_b32 s25, s21, s72
	v_lshl_add_u64 v[150:151], s[22:23], 0, v[144:145]
	s_add_i32 m0, s38, 0xc000
	ds_read_b128 v[188:191], v153
	ds_read_b128 v[192:195], v153 offset:1024
	ds_read_b128 v[196:199], v153 offset:2048
	ds_read_b128 v[200:203], v153 offset:3072
	ds_read_b128 v[204:207], v153 offset:4096
	ds_read_b128 v[208:211], v153 offset:5120
	ds_read_b128 v[212:215], v153 offset:6144
	ds_read_b128 v[216:219], v153 offset:7168
	global_load_lds_dwordx4 v[150:151], off
	v_lshl_add_u64 v[150:151], s[22:23], 0, v[146:147]
	s_add_i32 m0, s38, 0xe000
	s_nop 0
	global_load_lds_dwordx4 v[150:151], off
	s_waitcnt vmcnt(8)
	s_waitcnt lgkmcnt(0)
	s_setprio 1
	s_barrier
	v_mfma_f32_16x16x32_bf16 v[126:129], v[154:157], v[188:191], v[126:129]
	v_mfma_f32_16x16x32_bf16 v[122:125], v[162:165], v[188:191], v[122:125]
	v_mfma_f32_16x16x32_bf16 v[110:113], v[154:157], v[196:199], v[110:113]
	v_mfma_f32_16x16x32_bf16 v[106:109], v[162:165], v[196:199], v[106:109]
	v_mfma_f32_16x16x32_bf16 v[94:97], v[154:157], v[204:207], v[94:97]
	v_mfma_f32_16x16x32_bf16 v[90:93], v[162:165], v[204:207], v[90:93]
	v_mfma_f32_16x16x32_bf16 v[78:81], v[154:157], v[212:215], v[78:81]
	v_mfma_f32_16x16x32_bf16 v[74:77], v[162:165], v[212:215], v[74:77]
	v_mfma_f32_16x16x32_bf16 v[126:129], v[158:161], v[192:195], v[126:129]
	v_mfma_f32_16x16x32_bf16 v[122:125], v[166:169], v[192:195], v[122:125]
	v_mfma_f32_16x16x32_bf16 v[110:113], v[158:161], v[200:203], v[110:113]
	v_mfma_f32_16x16x32_bf16 v[106:109], v[166:169], v[200:203], v[106:109]
	v_mfma_f32_16x16x32_bf16 v[94:97], v[158:161], v[208:211], v[94:97]
	v_mfma_f32_16x16x32_bf16 v[90:93], v[166:169], v[208:211], v[90:93]
	v_mfma_f32_16x16x32_bf16 v[78:81], v[158:161], v[216:219], v[78:81]
	v_mfma_f32_16x16x32_bf16 v[74:77], v[166:169], v[216:219], v[74:77]
	v_mfma_f32_16x16x32_bf16 v[118:121], v[170:173], v[188:191], v[118:121]
	v_mfma_f32_16x16x32_bf16 v[114:117], v[180:183], v[188:191], v[114:117]
	v_mfma_f32_16x16x32_bf16 v[102:105], v[170:173], v[196:199], v[102:105]
	v_mfma_f32_16x16x32_bf16 v[98:101], v[180:183], v[196:199], v[98:101]
	v_mfma_f32_16x16x32_bf16 v[86:89], v[170:173], v[204:207], v[86:89]
	v_mfma_f32_16x16x32_bf16 v[82:85], v[180:183], v[204:207], v[82:85]
	v_mfma_f32_16x16x32_bf16 v[70:73], v[170:173], v[212:215], v[70:73]
	v_mfma_f32_16x16x32_bf16 v[66:69], v[180:183], v[212:215], v[66:69]
	v_mfma_f32_16x16x32_bf16 v[118:121], v[176:179], v[192:195], v[118:121]
	v_mfma_f32_16x16x32_bf16 v[114:117], v[184:187], v[192:195], v[114:117]
	v_mfma_f32_16x16x32_bf16 v[102:105], v[176:179], v[200:203], v[102:105]
	v_mfma_f32_16x16x32_bf16 v[98:101], v[184:187], v[200:203], v[98:101]
	v_mfma_f32_16x16x32_bf16 v[86:89], v[176:179], v[208:211], v[86:89]
	v_mfma_f32_16x16x32_bf16 v[82:85], v[184:187], v[208:211], v[82:85]
	v_mfma_f32_16x16x32_bf16 v[70:73], v[176:179], v[216:219], v[70:73]
	v_mfma_f32_16x16x32_bf16 v[66:69], v[184:187], v[216:219], v[66:69]
	s_barrier
	s_setprio 0
	s_add_i32 s74, s57, s37
	v_lshl_add_u64 v[150:151], s[24:25], 0, v[136:137]
	s_mov_b32 m0, s74
	ds_read_b128 v[188:191], v153 offset:16384
	ds_read_b128 v[192:195], v153 offset:17408
	ds_read_b128 v[196:199], v153 offset:18432
	ds_read_b128 v[200:203], v153 offset:19456
	ds_read_b128 v[204:207], v153 offset:20480
	ds_read_b128 v[208:211], v153 offset:21504
	ds_read_b128 v[212:215], v153 offset:22528
	ds_read_b128 v[216:219], v153 offset:23552
	global_load_lds_dwordx4 v[150:151], off
	s_add_i32 m0, s74, 0x2000
	s_add_u32 s74, s24, 0x2b0000
	v_lshl_add_u64 v[220:221], s[24:25], 0, v[130:131]
	s_addc_u32 s75, s25, 0
	s_add_i32 s76, s58, s37
	global_load_lds_dwordx4 v[220:221], off
	v_lshl_add_u64 v[222:223], s[74:75], 0, v[136:137]
	s_mov_b32 m0, s76
	v_lshl_add_u64 v[224:225], s[26:27], 0, v[132:133]
	global_load_lds_dwordx4 v[222:223], off
	v_lshl_add_u64 v[222:223], s[74:75], 0, v[130:131]
	s_add_i32 m0, s76, 0x2000
	s_nop 0
	global_load_lds_dwordx4 v[222:223], off
	v_lshl_add_u64 v[222:223], s[26:27], 0, v[138:139]
	s_mov_b32 m0, s38
	s_nop 0
	global_load_lds_dwordx4 v[222:223], off
	s_mov_b32 m0, s39
	s_nop 0
	global_load_lds_dwordx4 v[224:225], off
	s_waitcnt vmcnt(8)
	s_waitcnt lgkmcnt(0)
	s_setprio 1
	s_barrier
	v_mfma_f32_16x16x32_bf16 v[62:65], v[154:157], v[188:191], v[62:65]
	v_mfma_f32_16x16x32_bf16 v[58:61], v[162:165], v[188:191], v[58:61]
	v_mfma_f32_16x16x32_bf16 v[46:49], v[154:157], v[196:199], v[46:49]
	v_mfma_f32_16x16x32_bf16 v[42:45], v[162:165], v[196:199], v[42:45]
	v_mfma_f32_16x16x32_bf16 v[30:33], v[154:157], v[204:207], v[30:33]
	v_mfma_f32_16x16x32_bf16 v[26:29], v[162:165], v[204:207], v[26:29]
	v_mfma_f32_16x16x32_bf16 v[14:17], v[154:157], v[212:215], v[14:17]
	v_mfma_f32_16x16x32_bf16 v[10:13], v[162:165], v[212:215], v[10:13]
	v_mfma_f32_16x16x32_bf16 v[62:65], v[158:161], v[192:195], v[62:65]
	v_mfma_f32_16x16x32_bf16 v[58:61], v[166:169], v[192:195], v[58:61]
	v_mfma_f32_16x16x32_bf16 v[46:49], v[158:161], v[200:203], v[46:49]
	v_mfma_f32_16x16x32_bf16 v[42:45], v[166:169], v[200:203], v[42:45]
	v_mfma_f32_16x16x32_bf16 v[30:33], v[158:161], v[208:211], v[30:33]
	v_mfma_f32_16x16x32_bf16 v[26:29], v[166:169], v[208:211], v[26:29]
	v_mfma_f32_16x16x32_bf16 v[14:17], v[158:161], v[216:219], v[14:17]
	v_mfma_f32_16x16x32_bf16 v[10:13], v[166:169], v[216:219], v[10:13]
	v_mfma_f32_16x16x32_bf16 v[54:57], v[170:173], v[188:191], v[54:57]
	v_mfma_f32_16x16x32_bf16 v[50:53], v[180:183], v[188:191], v[50:53]
	v_mfma_f32_16x16x32_bf16 v[38:41], v[170:173], v[196:199], v[38:41]
	v_mfma_f32_16x16x32_bf16 v[34:37], v[180:183], v[196:199], v[34:37]
	v_mfma_f32_16x16x32_bf16 v[22:25], v[170:173], v[204:207], v[22:25]
	v_mfma_f32_16x16x32_bf16 v[18:21], v[180:183], v[204:207], v[18:21]
	v_mfma_f32_16x16x32_bf16 v[6:9], v[170:173], v[212:215], v[6:9]
	v_mfma_f32_16x16x32_bf16 v[2:5], v[180:183], v[212:215], v[2:5]
	v_mfma_f32_16x16x32_bf16 v[54:57], v[176:179], v[192:195], v[54:57]
	v_mfma_f32_16x16x32_bf16 v[50:53], v[184:187], v[192:195], v[50:53]
	v_mfma_f32_16x16x32_bf16 v[38:41], v[176:179], v[200:203], v[38:41]
	v_mfma_f32_16x16x32_bf16 v[34:37], v[184:187], v[200:203], v[34:37]
	v_mfma_f32_16x16x32_bf16 v[22:25], v[176:179], v[208:211], v[22:25]
	v_mfma_f32_16x16x32_bf16 v[18:21], v[184:187], v[208:211], v[18:21]
	v_mfma_f32_16x16x32_bf16 v[6:9], v[176:179], v[216:219], v[6:9]
	v_mfma_f32_16x16x32_bf16 v[2:5], v[184:187], v[216:219], v[2:5]
	s_barrier
	s_setprio 0
	s_add_i32 s74, 0, 0x18000
	s_add_i32 s75, 0, 0x1c000
	v_add_u32_e32 v166, s74, v1
	v_add_u32_e32 v175, s75, v1
	ds_read_b128 v[154:157], v166
	ds_read_b128 v[158:161], v166 offset:1024
	ds_read_b128 v[162:165], v166 offset:2048
	ds_read_b128 v[166:169], v166 offset:3072
	ds_read_b128 v[170:173], v175
	ds_read_b128 v[176:179], v175 offset:1024
	ds_read_b128 v[180:183], v175 offset:2048
	ds_read_b128 v[184:187], v175 offset:3072
	s_add_u32 s26, s26, 0x2b0000
	s_addc_u32 s27, s27, 0
	s_mov_b32 m0, s40
	v_lshl_add_u64 v[226:227], s[26:27], 0, v[138:139]
	ds_read_b128 v[188:191], v153 offset:32768
	ds_read_b128 v[192:195], v153 offset:33792
	ds_read_b128 v[196:199], v153 offset:34816
	ds_read_b128 v[200:203], v153 offset:35840
	ds_read_b128 v[204:207], v153 offset:36864
	ds_read_b128 v[208:211], v153 offset:37888
	ds_read_b128 v[212:215], v153 offset:38912
	ds_read_b128 v[216:219], v153 offset:39936
	global_load_lds_dwordx4 v[226:227], off
	v_lshl_add_u64 v[226:227], s[26:27], 0, v[132:133]
	s_mov_b32 m0, s41
	s_nop 0
	global_load_lds_dwordx4 v[226:227], off
	s_waitcnt vmcnt(8)
	s_waitcnt lgkmcnt(0)
	s_setprio 1
	s_barrier
	v_mfma_f32_16x16x32_bf16 v[126:129], v[154:157], v[188:191], v[126:129]
	v_mfma_f32_16x16x32_bf16 v[122:125], v[162:165], v[188:191], v[122:125]
	v_mfma_f32_16x16x32_bf16 v[110:113], v[154:157], v[196:199], v[110:113]
	v_mfma_f32_16x16x32_bf16 v[106:109], v[162:165], v[196:199], v[106:109]
	v_mfma_f32_16x16x32_bf16 v[94:97], v[154:157], v[204:207], v[94:97]
	v_mfma_f32_16x16x32_bf16 v[90:93], v[162:165], v[204:207], v[90:93]
	v_mfma_f32_16x16x32_bf16 v[78:81], v[154:157], v[212:215], v[78:81]
	v_mfma_f32_16x16x32_bf16 v[74:77], v[162:165], v[212:215], v[74:77]
	v_mfma_f32_16x16x32_bf16 v[126:129], v[158:161], v[192:195], v[126:129]
	v_mfma_f32_16x16x32_bf16 v[122:125], v[166:169], v[192:195], v[122:125]
	v_mfma_f32_16x16x32_bf16 v[110:113], v[158:161], v[200:203], v[110:113]
	v_mfma_f32_16x16x32_bf16 v[106:109], v[166:169], v[200:203], v[106:109]
	v_mfma_f32_16x16x32_bf16 v[94:97], v[158:161], v[208:211], v[94:97]
	v_mfma_f32_16x16x32_bf16 v[90:93], v[166:169], v[208:211], v[90:93]
	v_mfma_f32_16x16x32_bf16 v[78:81], v[158:161], v[216:219], v[78:81]
	v_mfma_f32_16x16x32_bf16 v[74:77], v[166:169], v[216:219], v[74:77]
	v_mfma_f32_16x16x32_bf16 v[118:121], v[170:173], v[188:191], v[118:121]
	v_mfma_f32_16x16x32_bf16 v[114:117], v[180:183], v[188:191], v[114:117]
	v_mfma_f32_16x16x32_bf16 v[102:105], v[170:173], v[196:199], v[102:105]
	v_mfma_f32_16x16x32_bf16 v[98:101], v[180:183], v[196:199], v[98:101]
	v_mfma_f32_16x16x32_bf16 v[86:89], v[170:173], v[204:207], v[86:89]
	v_mfma_f32_16x16x32_bf16 v[82:85], v[180:183], v[204:207], v[82:85]
	v_mfma_f32_16x16x32_bf16 v[70:73], v[170:173], v[212:215], v[70:73]
	v_mfma_f32_16x16x32_bf16 v[66:69], v[180:183], v[212:215], v[66:69]
	v_mfma_f32_16x16x32_bf16 v[118:121], v[176:179], v[192:195], v[118:121]
	v_mfma_f32_16x16x32_bf16 v[114:117], v[184:187], v[192:195], v[114:117]
	v_mfma_f32_16x16x32_bf16 v[102:105], v[176:179], v[200:203], v[102:105]
	v_mfma_f32_16x16x32_bf16 v[98:101], v[184:187], v[200:203], v[98:101]
	v_mfma_f32_16x16x32_bf16 v[86:89], v[176:179], v[208:211], v[86:89]
	v_mfma_f32_16x16x32_bf16 v[82:85], v[184:187], v[208:211], v[82:85]
	v_mfma_f32_16x16x32_bf16 v[70:73], v[176:179], v[216:219], v[70:73]
	v_mfma_f32_16x16x32_bf16 v[66:69], v[184:187], v[216:219], v[66:69]
	s_barrier
	s_setprio 0
	s_add_i32 s26, s74, s37
	v_lshl_add_u64 v[150:151], v[150:151], 0, s[6:7]
	s_mov_b32 m0, s26
	ds_read_b128 v[188:191], v153 offset:49152
	ds_read_b128 v[192:195], v153 offset:50176
	ds_read_b128 v[196:199], v153 offset:51200
	ds_read_b128 v[200:203], v153 offset:52224
	ds_read_b128 v[204:207], v153 offset:53248
	ds_read_b128 v[208:211], v153 offset:54272
	ds_read_b128 v[212:215], v153 offset:55296
	ds_read_b128 v[216:219], v153 offset:56320
	global_load_lds_dwordx4 v[150:151], off
	s_add_i32 m0, s26, 0x2000
	s_add_u32 s24, s24, 0x2b0080
	v_lshl_add_u64 v[150:151], v[220:221], 0, s[6:7]
	s_addc_u32 s25, s25, 0
	s_add_i32 s26, s75, s37
	global_load_lds_dwordx4 v[150:151], off
	v_lshl_add_u64 v[150:151], s[24:25], 0, v[136:137]
	s_mov_b32 m0, s26
	s_nop 0
	global_load_lds_dwordx4 v[150:151], off
	v_lshl_add_u64 v[150:151], s[24:25], 0, v[130:131]
	s_add_i32 m0, s26, 0x2000
	s_nop 0
	global_load_lds_dwordx4 v[150:151], off
	v_lshl_add_u64 v[150:151], v[222:223], 0, s[6:7]
	s_mov_b32 m0, s54
	s_nop 0
	global_load_lds_dwordx4 v[150:151], off
	v_lshl_add_u64 v[150:151], v[224:225], 0, s[6:7]
	s_mov_b32 m0, s55
	s_nop 0
	global_load_lds_dwordx4 v[150:151], off
	s_waitcnt vmcnt(8)
	s_waitcnt lgkmcnt(0)
	s_setprio 1
	s_barrier
	v_mfma_f32_16x16x32_bf16 v[62:65], v[154:157], v[188:191], v[62:65]
	v_mfma_f32_16x16x32_bf16 v[58:61], v[162:165], v[188:191], v[58:61]
	v_mfma_f32_16x16x32_bf16 v[46:49], v[154:157], v[196:199], v[46:49]
	v_mfma_f32_16x16x32_bf16 v[42:45], v[162:165], v[196:199], v[42:45]
	v_mfma_f32_16x16x32_bf16 v[30:33], v[154:157], v[204:207], v[30:33]
	v_mfma_f32_16x16x32_bf16 v[26:29], v[162:165], v[204:207], v[26:29]
	v_mfma_f32_16x16x32_bf16 v[14:17], v[154:157], v[212:215], v[14:17]
	v_mfma_f32_16x16x32_bf16 v[10:13], v[162:165], v[212:215], v[10:13]
	v_mfma_f32_16x16x32_bf16 v[62:65], v[158:161], v[192:195], v[62:65]
	v_mfma_f32_16x16x32_bf16 v[58:61], v[166:169], v[192:195], v[58:61]
	v_mfma_f32_16x16x32_bf16 v[46:49], v[158:161], v[200:203], v[46:49]
	v_mfma_f32_16x16x32_bf16 v[42:45], v[166:169], v[200:203], v[42:45]
	v_mfma_f32_16x16x32_bf16 v[30:33], v[158:161], v[208:211], v[30:33]
	v_mfma_f32_16x16x32_bf16 v[26:29], v[166:169], v[208:211], v[26:29]
	v_mfma_f32_16x16x32_bf16 v[14:17], v[158:161], v[216:219], v[14:17]
	v_mfma_f32_16x16x32_bf16 v[10:13], v[166:169], v[216:219], v[10:13]
	v_mfma_f32_16x16x32_bf16 v[54:57], v[170:173], v[188:191], v[54:57]
	v_mfma_f32_16x16x32_bf16 v[50:53], v[180:183], v[188:191], v[50:53]
	v_mfma_f32_16x16x32_bf16 v[38:41], v[170:173], v[196:199], v[38:41]
	v_mfma_f32_16x16x32_bf16 v[34:37], v[180:183], v[196:199], v[34:37]
	v_mfma_f32_16x16x32_bf16 v[22:25], v[170:173], v[204:207], v[22:25]
	v_mfma_f32_16x16x32_bf16 v[18:21], v[180:183], v[204:207], v[18:21]
	v_mfma_f32_16x16x32_bf16 v[6:9], v[170:173], v[212:215], v[6:9]
	v_mfma_f32_16x16x32_bf16 v[2:5], v[180:183], v[212:215], v[2:5]
	v_mfma_f32_16x16x32_bf16 v[54:57], v[176:179], v[192:195], v[54:57]
	v_mfma_f32_16x16x32_bf16 v[50:53], v[184:187], v[192:195], v[50:53]
	v_mfma_f32_16x16x32_bf16 v[38:41], v[176:179], v[200:203], v[38:41]
	v_mfma_f32_16x16x32_bf16 v[34:37], v[184:187], v[200:203], v[34:37]
	v_mfma_f32_16x16x32_bf16 v[22:25], v[176:179], v[208:211], v[22:25]
	v_mfma_f32_16x16x32_bf16 v[18:21], v[184:187], v[208:211], v[18:21]
	v_mfma_f32_16x16x32_bf16 v[6:9], v[176:179], v[216:219], v[6:9]
	v_mfma_f32_16x16x32_bf16 v[2:5], v[184:187], v[216:219], v[2:5]
	s_barrier
	s_setprio 0
	s_add_u32 s22, s22, 0x100
	s_addc_u32 s23, s23, 0
	s_add_u32 s71, s71, 0x100
	s_addc_u32 s72, s72, 0
	s_cmp_ge_u32 s73, s2
	s_mov_b32 s24, s73
	s_cbranch_scc0 .LBB0_931
	s_ashr_i32 s2, s69, 20
	s_cmp_gt_i32 s2, 0
	s_mov_b64 s[22:23], -1
	s_cbranch_scc0 .LBB0_934
